# v3: resnorm rows software-pipelined (next row prefetched before this row's write-through stores, gain vectors loaded once) + s5 pass2 backward read-back wait moved behind the recurrence
# speedup vs baseline: 1.0027x; 1.0027x over previous
; #define LAS __attribute__((address_space(3)))
; __device__ __forceinline__ unsigned cvtpk(float lo, float hi) { typedef __bf16 bf2 __attribute__((ext_vector_type(2))); f32x2 v = {lo, hi}; bf2 b = __builtin_convertvector(v, bf2); return __builtin_bit_cast(unsigned, b); }
; template <int DIR, bool PASS2>
; __device__ __forceinline__ void s5_sub(LAS unsigned char* ulds, const bf16x8 (&bb)[8], const bf16x8 (&bc)[4], float lbr, float lbi, float& sr, float& si, f32x4& yacc, int sub, int lane) {
;     ...
;     u32x4 uw = {0u, 0u, 0u, 0u};
;     if (kq < 2) uw = *(const LAS u32x4*)(ulds + (sub * 16 + hq) * 32 + kq * 16);
;     const bf16x8 ua = __builtin_bit_cast(bf16x8, uw);
;     LAS float* xp = xlds + (4 * kq) * S5_XP + hq;
;     f32x4 xs[8];
; #pragma unroll
;     for (int nt = 0; nt < 8; ++nt) xs[nt] = __builtin_amdgcn_mfma_f32_16x16x32_bf16(ua, bb[nt], (f32x4){0.f, 0.f, 0.f, 0.f}, 0, 0, 0);
;     asm volatile("s_nop 15\n\ts_nop 15" : "+v"(xs[0]), "+v"(xs[1]), "+v"(xs[2]), "+v"(xs[3]), "+v"(xs[4]), "+v"(xs[5]), "+v"(xs[6]), "+v"(xs[7]));
; #pragma unroll
;     for (int nt = 0; nt < 8; ++nt) { xp[16 * nt] = xs[nt][0]; xp[16 * nt + S5_XP] = xs[nt][1]; xp[16 * nt + 2 * S5_XP] = xs[nt][2]; xp[16 * nt + 3 * S5_XP] = xs[nt][3]; }
;     asm volatile("s_waitcnt lgkmcnt(0)" ::: "memory");
;     const LAS float* xr = xlds + 2 * lane; LAS unsigned char* sw = slds + lane * 4;
; #pragma unroll
;     for (int q = 0; q < 16; ++q) {
;         const int jj = DIR ? 15 - q : q;
;         const f32x2 x = *(const LAS f32x2*)(xr + jj * S5_XP);
;         const float nr = lbr * sr - lbi * si + x[0], ni = lbr * si + lbi * sr + x[1]; sr = nr; si = ni;
;         if (PASS2) *(LAS unsigned*)(sw + jj * 272) = cvtpk(sr, si);
;     }
; __device__ __forceinline__ void s5h_pass2(PPtr P, int li, LAS unsigned char* lds, int gw, int NGW, int wave, int lane) {
;     ...
;                 bf16_t* drow = dst + (size_t)(sub * 16 + 4 * kq) * LDP;
;                 float yf[4] = {0.f, 0.f, 0.f, 0.f};
;                 if (dir) {
; #pragma unroll
;                     for (int i = 0; i < 4; ++i) yf[i] = bf1(drow[(size_t)i * LDP]);
;                 }
;                 f32x4 acc = {0.f, 0.f, 0.f, 0.f};
;                 if (dir == 0) s5_sub<0, true>(ulds, bb, bc, lbr, lbi, sr, si, acc, sub, lane); else s5_sub<1, true>(ulds, bb, bc, lbr, lbi, sr, si, acc, sub, lane);
.LBB0_493:
	s_and_b64 s[10:11], s[50:51], exec
	s_cselect_b32 s10, s38, s68
	v_lshl_or_b32 v64, s10, 4, v78
	v_mul_lo_u32 v68, v64, s70
	v_cndmask_b32_e64 v50, 0, 1, s[64:65]
	v_lshl_add_u64 v[56:57], v[68:69], 1, v[96:97]
	v_cmp_ne_u32_e64 s[10:11], 1, v50
	s_andn2_b64 vcc, exec, s[64:65]
	s_mov_b64 s[66:67], -1
	s_cbranch_vccnz .LBB0_499
	v_add_co_u32_e32 v50, vcc, 0x1000, v56
	s_nop 1
	v_addc_co_u32_e32 v51, vcc, 0, v57, vcc
	v_add_co_u32_e32 v52, vcc, 0x3000, v56
	s_nop 1
	v_addc_co_u32_e32 v53, vcc, 0, v57, vcc
	v_add_co_u32_e32 v62, vcc, 0x4000, v56
	s_nop 1
	v_addc_co_u32_e32 v63, vcc, 0, v57, vcc
	global_load_ushort v60, v[56:57], off
	global_load_ushort v58, v[50:51], off offset:2368
	global_load_ushort v59, v[52:53], off offset:640
	global_load_ushort v65, v[62:63], off offset:3008
	v_mov_b32_e32 v50, 0
	v_mov_b32_e32 v51, 0
	v_mov_b32_e32 v52, 0
	v_mov_b32_e32 v53, 0
	s_and_saveexec_b64 s[66:67], s[8:9]
	ds_read_b128 v[50:53], v93
	s_or_b64 exec, exec, s[66:67]
	s_waitcnt lgkmcnt(0)
	v_mfma_f32_16x16x32_bf16 v[110:113], v[50:53], v[2:5], 0
	v_add_u32_e32 v61, v67, v73
	v_add_u32_e32 v62, 0x1000, v61
	v_add_u32_e32 v61, 0x1400, v61
	v_mfma_f32_16x16x32_bf16 v[128:131], v[50:53], v[6:9], 0
	v_mul_f32_e32 v68, v105, v106
	v_add_u32_e32 v114, s27, v77
	v_mfma_f32_16x16x32_bf16 v[132:135], v[50:53], v[10:13], 0
	v_mfma_f32_16x16x32_bf16 v[136:139], v[50:53], v[14:17], 0
	v_mfma_f32_16x16x32_bf16 v[140:143], v[50:53], v[18:21], 0
	v_mfma_f32_16x16x32_bf16 v[144:147], v[50:53], v[22:25], 0
	v_mfma_f32_16x16x32_bf16 v[148:151], v[50:53], v[26:29], 0
	v_mfma_f32_16x16x32_bf16 v[50:53], v[50:53], v[30:33], 0
	s_nop 15
	s_nop 15
	ds_write2_b32 v62, v110, v128 offset1:16
	ds_write2_b32 v62, v111, v129 offset0:132 offset1:148
	ds_write2_b32 v61, v112, v130 offset0:8 offset1:24
	ds_write2_b32 v61, v113, v131 offset0:140 offset1:156
	ds_write2_b32 v62, v132, v136 offset0:32 offset1:48
	ds_write2_b32 v62, v133, v137 offset0:164 offset1:180
	ds_write2_b32 v61, v134, v138 offset0:40 offset1:56
	ds_write2_b32 v61, v135, v139 offset0:172 offset1:188
	ds_write2_b32 v62, v140, v144 offset0:64 offset1:80
	ds_write2_b32 v62, v141, v145 offset0:196 offset1:212
	ds_write2_b32 v61, v142, v146 offset0:72 offset1:88
	ds_write2_b32 v61, v143, v147 offset0:204 offset1:220
	ds_write2_b32 v62, v148, v50 offset0:96 offset1:112
	ds_write2_b32 v62, v149, v51 offset0:228 offset1:244
	ds_write2_b32 v61, v150, v52 offset0:104 offset1:120
	ds_write2_b32 v61, v151, v53 offset0:236 offset1:252
	v_add_u32_e32 v61, s27, v72
	s_waitcnt lgkmcnt(0)
	v_add_u32_e32 v109, 0x2800, v61
	ds_read2_b64 v[50:53], v109 offset0:156 offset1:222
	v_mul_f32_e32 v62, v105, v107
	v_pk_fma_f32 v[62:63], v[104:105], v[106:107], v[62:63] op_sel_hi:[1,1,0] neg_lo:[0,0,1] neg_hi:[0,0,1]
	v_pk_fma_f32 v[110:111], v[104:105], v[106:107], v[68:69] op_sel:[0,1,0] op_sel_hi:[1,0,0]
	v_add_u32_e32 v115, 0x2000, v61
	s_waitcnt lgkmcnt(0)
	v_pk_add_f32 v[62:63], v[62:63], v[52:53]
	v_pk_add_f32 v[52:53], v[110:111], v[52:53] op_sel:[0,1] op_sel_hi:[1,0]
	s_nop 0
	v_mov_b32_e32 v63, v52
	v_mul_f32_e32 v68, v105, v52
	v_cvt_pk_bf16_f32 v112, v62, v52
	v_pk_fma_f32 v[110:111], v[104:105], v[62:63], v[68:69] op_sel_hi:[1,1,0] neg_lo:[0,0,1] neg_hi:[0,0,1]
	v_mov_b32_e32 v53, v62
	v_mul_f32_e32 v62, v105, v62
	v_pk_fma_f32 v[52:53], v[104:105], v[52:53], v[62:63] op_sel_hi:[1,1,0]
	v_pk_add_f32 v[110:111], v[50:51], v[110:111]
	v_pk_add_f32 v[62:63], v[50:51], v[52:53] op_sel:[1,0] op_sel_hi:[0,1]
	ds_read2_b64 v[50:53], v109 offset0:24 offset1:90
	v_cvt_pk_bf16_f32 v63, v110, v62
	v_add_u32_e32 v68, 0x3e00, v114
	v_mov_b32_e32 v111, v62
	ds_write2_b32 v68, v63, v112 offset0:120 offset1:188
	v_mul_f32_e32 v68, v105, v62
	v_pk_fma_f32 v[112:113], v[104:105], v[110:111], v[68:69] op_sel_hi:[1,1,0] neg_lo:[0,0,1] neg_hi:[0,0,1]
	v_mov_b32_e32 v63, v110
	v_mul_f32_e32 v68, v105, v110
	v_pk_fma_f32 v[62:63], v[104:105], v[62:63], v[68:69] op_sel_hi:[1,1,0]
	s_waitcnt lgkmcnt(1)
	v_pk_add_f32 v[112:113], v[52:53], v[112:113]
	v_pk_add_f32 v[52:53], v[52:53], v[62:63] op_sel:[1,0] op_sel_hi:[0,1]
	v_mov_b32_e32 v113, v52
	v_mul_f32_e32 v62, v105, v52
	v_mov_b32_e32 v53, v112
	v_mul_f32_e32 v68, v105, v112
	v_cvt_pk_bf16_f32 v109, v112, v52
	v_pk_fma_f32 v[62:63], v[104:105], v[112:113], v[62:63] op_sel_hi:[1,1,0] neg_lo:[0,0,1] neg_hi:[0,0,1]
	v_pk_fma_f32 v[52:53], v[104:105], v[52:53], v[68:69] op_sel_hi:[1,1,0]
	v_pk_add_f32 v[62:63], v[50:51], v[62:63]
	v_pk_add_f32 v[110:111], v[50:51], v[52:53] op_sel:[1,0] op_sel_hi:[0,1]
	ds_read2_b64 v[50:53], v115 offset0:148 offset1:214
	v_cvt_pk_bf16_f32 v68, v62, v110
	v_add_u32_e32 v111, 0x3c00, v114
	v_mov_b32_e32 v63, v110
	ds_write2_b32 v111, v68, v109 offset0:112 offset1:180
	v_mul_f32_e32 v68, v105, v110
	v_pk_fma_f32 v[112:113], v[104:105], v[62:63], v[68:69] op_sel_hi:[1,1,0] neg_lo:[0,0,1] neg_hi:[0,0,1]
	v_mov_b32_e32 v111, v62
	v_mul_f32_e32 v62, v105, v62
	v_pk_fma_f32 v[62:63], v[104:105], v[110:111], v[62:63] op_sel_hi:[1,1,0]
	s_waitcnt lgkmcnt(1)
	v_pk_add_f32 v[112:113], v[52:53], v[112:113]
	v_pk_add_f32 v[52:53], v[52:53], v[62:63] op_sel:[1,0] op_sel_hi:[0,1]
	v_mov_b32_e32 v113, v52
	v_mul_f32_e32 v62, v105, v52
	v_mov_b32_e32 v53, v112
	v_mul_f32_e32 v68, v105, v112
	v_cvt_pk_bf16_f32 v109, v112, v52
	v_pk_fma_f32 v[62:63], v[104:105], v[112:113], v[62:63] op_sel_hi:[1,1,0] neg_lo:[0,0,1] neg_hi:[0,0,1]
	v_pk_fma_f32 v[52:53], v[104:105], v[52:53], v[68:69] op_sel_hi:[1,1,0]
	v_pk_add_f32 v[62:63], v[50:51], v[62:63]
	v_pk_add_f32 v[110:111], v[50:51], v[52:53] op_sel:[1,0] op_sel_hi:[0,1]
	ds_read2_b64 v[50:53], v115 offset0:16 offset1:82
	v_cvt_pk_bf16_f32 v68, v62, v110
	v_add_u32_e32 v111, 0x3a00, v114
	v_mov_b32_e32 v63, v110
	ds_write2_b32 v111, v68, v109 offset0:104 offset1:172
	v_mul_f32_e32 v68, v105, v110
	v_pk_fma_f32 v[112:113], v[104:105], v[62:63], v[68:69] op_sel_hi:[1,1,0] neg_lo:[0,0,1] neg_hi:[0,0,1]
	v_mov_b32_e32 v111, v62
	v_mul_f32_e32 v62, v105, v62
	v_pk_fma_f32 v[62:63], v[104:105], v[110:111], v[62:63] op_sel_hi:[1,1,0]
	s_waitcnt lgkmcnt(1)
; #define LAS __attribute__((address_space(3)))
; __device__ __forceinline__ unsigned cvtpk(float lo, float hi) { typedef __bf16 bf2 __attribute__((ext_vector_type(2))); f32x2 v = {lo, hi}; bf2 b = __builtin_convertvector(v, bf2); return __builtin_bit_cast(unsigned, b); }
; template <int DIR, bool PASS2>
; __device__ __forceinline__ void s5_sub(LAS unsigned char* ulds, const bf16x8 (&bb)[8], const bf16x8 (&bc)[4], float lbr, float lbi, float& sr, float& si, f32x4& yacc, int sub, int lane) {
;     ...
;     const LAS float* xr = xlds + 2 * lane; LAS unsigned char* sw = slds + lane * 4;
; #pragma unroll
;     for (int q = 0; q < 16; ++q) {
;         const int jj = DIR ? 15 - q : q;
;         const f32x2 x = *(const LAS f32x2*)(xr + jj * S5_XP);
;         const float nr = lbr * sr - lbi * si + x[0], ni = lbr * si + lbi * sr + x[1]; sr = nr; si = ni;
;         if (PASS2) *(LAS unsigned*)(sw + jj * 272) = cvtpk(sr, si);
;     }
;     if (PASS2) {
;         asm volatile("s_waitcnt lgkmcnt(0)" ::: "memory");
;         f32x4 acc = DIR ? yacc : (f32x4){0.f, 0.f, 0.f, 0.f};
;         const LAS unsigned char* sa = slds + hq * 272 + kq * 16;
; #pragma unroll
;         for (int ks = 0; ks < 4; ++ks) { const bf16x8 a = *(const LAS bf16x8*)(sa + ks * 64); acc = __builtin_amdgcn_mfma_f32_16x16x32_bf16(a, bc[ks], acc, 0, 0, 0); }
;         yacc = acc;
; __device__ __forceinline__ void s5h_pass2(PPtr P, int li, LAS unsigned char* lds, int gw, int NGW, int wave, int lane) {
;     ...
;                 if (dir) {
; #pragma unroll
;                     for (int i = 0; i < 4; ++i) yf[i] = bf1(drow[(size_t)i * LDP]);
;                 }
	v_pk_add_f32 v[112:113], v[52:53], v[112:113]
	v_pk_add_f32 v[52:53], v[52:53], v[62:63] op_sel:[1,0] op_sel_hi:[0,1]
	v_mov_b32_e32 v113, v52
	v_mul_f32_e32 v62, v105, v52
	v_mov_b32_e32 v53, v112
	v_mul_f32_e32 v68, v105, v112
	v_cvt_pk_bf16_f32 v109, v112, v52
	v_pk_fma_f32 v[62:63], v[104:105], v[112:113], v[62:63] op_sel_hi:[1,1,0] neg_lo:[0,0,1] neg_hi:[0,0,1]
	v_pk_fma_f32 v[52:53], v[104:105], v[52:53], v[68:69] op_sel_hi:[1,1,0]
	v_add_u32_e32 v115, 0x1800, v61
	v_pk_add_f32 v[62:63], v[50:51], v[62:63]
	v_pk_add_f32 v[110:111], v[50:51], v[52:53] op_sel:[1,0] op_sel_hi:[0,1]
	ds_read2_b64 v[50:53], v115 offset0:140 offset1:206
	v_cvt_pk_bf16_f32 v68, v62, v110
	v_add_u32_e32 v111, 0x3800, v114
	v_mov_b32_e32 v63, v110
	ds_write2_b32 v111, v68, v109 offset0:96 offset1:164
	v_mul_f32_e32 v68, v105, v110
	v_pk_fma_f32 v[112:113], v[104:105], v[62:63], v[68:69] op_sel_hi:[1,1,0] neg_lo:[0,0,1] neg_hi:[0,0,1]
	v_mov_b32_e32 v111, v62
	v_mul_f32_e32 v62, v105, v62
	v_pk_fma_f32 v[62:63], v[104:105], v[110:111], v[62:63] op_sel_hi:[1,1,0]
	s_waitcnt lgkmcnt(1)
	v_pk_add_f32 v[112:113], v[52:53], v[112:113]
	v_pk_add_f32 v[52:53], v[52:53], v[62:63] op_sel:[1,0] op_sel_hi:[0,1]
	v_mov_b32_e32 v113, v52
	v_mul_f32_e32 v62, v105, v52
	v_mov_b32_e32 v53, v112
	v_mul_f32_e32 v68, v105, v112
	v_cvt_pk_bf16_f32 v109, v112, v52
	v_pk_fma_f32 v[62:63], v[104:105], v[112:113], v[62:63] op_sel_hi:[1,1,0] neg_lo:[0,0,1] neg_hi:[0,0,1]
	v_pk_fma_f32 v[52:53], v[104:105], v[52:53], v[68:69] op_sel_hi:[1,1,0]
	v_pk_add_f32 v[62:63], v[50:51], v[62:63]
	v_pk_add_f32 v[110:111], v[50:51], v[52:53] op_sel:[1,0] op_sel_hi:[0,1]
	ds_read2_b64 v[50:53], v115 offset0:8 offset1:74
	v_cvt_pk_bf16_f32 v68, v62, v110
	v_add_u32_e32 v111, 0x3600, v114
	v_mov_b32_e32 v63, v110
	ds_write2_b32 v111, v68, v109 offset0:88 offset1:156
	v_mul_f32_e32 v68, v105, v110
	v_pk_fma_f32 v[112:113], v[104:105], v[62:63], v[68:69] op_sel_hi:[1,1,0] neg_lo:[0,0,1] neg_hi:[0,0,1]
	v_mov_b32_e32 v111, v62
	v_mul_f32_e32 v62, v105, v62
	v_pk_fma_f32 v[62:63], v[104:105], v[110:111], v[62:63] op_sel_hi:[1,1,0]
	s_waitcnt lgkmcnt(1)
	v_pk_add_f32 v[112:113], v[52:53], v[112:113]
	v_pk_add_f32 v[52:53], v[52:53], v[62:63] op_sel:[1,0] op_sel_hi:[0,1]
	v_mov_b32_e32 v113, v52
	v_mul_f32_e32 v62, v105, v52
	v_mov_b32_e32 v53, v112
	v_mul_f32_e32 v68, v105, v112
	v_cvt_pk_bf16_f32 v109, v112, v52
	v_pk_fma_f32 v[62:63], v[104:105], v[112:113], v[62:63] op_sel_hi:[1,1,0] neg_lo:[0,0,1] neg_hi:[0,0,1]
	v_pk_fma_f32 v[52:53], v[104:105], v[52:53], v[68:69] op_sel_hi:[1,1,0]
	v_add_u32_e32 v61, 0x1000, v61
	v_pk_add_f32 v[62:63], v[50:51], v[62:63]
	v_pk_add_f32 v[110:111], v[50:51], v[52:53] op_sel:[1,0] op_sel_hi:[0,1]
	ds_read2_b64 v[50:53], v61 offset0:132 offset1:198
	v_cvt_pk_bf16_f32 v68, v62, v110
	v_add_u32_e32 v111, 0x3400, v114
	v_mov_b32_e32 v63, v110
	ds_write2_b32 v111, v68, v109 offset0:80 offset1:148
	v_mul_f32_e32 v68, v105, v110
	v_pk_fma_f32 v[112:113], v[104:105], v[62:63], v[68:69] op_sel_hi:[1,1,0] neg_lo:[0,0,1] neg_hi:[0,0,1]
	v_mov_b32_e32 v111, v62
	v_mul_f32_e32 v62, v105, v62
	v_pk_fma_f32 v[62:63], v[104:105], v[110:111], v[62:63] op_sel_hi:[1,1,0]
	s_waitcnt lgkmcnt(1)
	v_pk_add_f32 v[112:113], v[52:53], v[112:113]
	v_pk_add_f32 v[52:53], v[52:53], v[62:63] op_sel:[1,0] op_sel_hi:[0,1]
	v_mov_b32_e32 v113, v52
	v_mul_f32_e32 v62, v105, v52
	v_mov_b32_e32 v53, v112
	v_mul_f32_e32 v68, v105, v112
	v_cvt_pk_bf16_f32 v109, v112, v52
	v_pk_fma_f32 v[62:63], v[104:105], v[112:113], v[62:63] op_sel_hi:[1,1,0] neg_lo:[0,0,1] neg_hi:[0,0,1]
	v_pk_fma_f32 v[52:53], v[104:105], v[52:53], v[68:69] op_sel_hi:[1,1,0]
	v_pk_add_f32 v[62:63], v[50:51], v[62:63]
	v_pk_add_f32 v[110:111], v[50:51], v[52:53] op_sel:[1,0] op_sel_hi:[0,1]
	v_cvt_pk_bf16_f32 v50, v62, v110
	v_add_u32_e32 v51, 0x3200, v114
	ds_write2_b32 v51, v50, v109 offset0:72 offset1:140
	ds_read2_b64 v[50:53], v61 offset1:66
	v_mov_b32_e32 v63, v110
	v_pk_mul_f32 v[112:113], v[104:105], v[62:63]
	v_mov_b32_e32 v111, v62
	v_mul_f32_e32 v62, v105, v62
	v_pk_fma_f32 v[62:63], v[104:105], v[110:111], v[62:63] op_sel_hi:[1,1,0]
	s_waitcnt lgkmcnt(0)
	v_pk_add_f32 v[62:63], v[52:53], v[62:63] op_sel:[1,0] op_sel_hi:[0,1]
	v_sub_f32_e32 v53, v112, v113
	v_add_f32_e32 v52, v52, v53
	v_cvt_pk_bf16_f32 v61, v52, v62
	v_pk_mul_f32 v[62:63], v[54:55], v[62:63] op_sel_hi:[1,0]
	s_nop 0
	v_pk_fma_f32 v[110:111], v[104:105], v[52:53], v[62:63] op_sel_hi:[1,0,1] neg_lo:[0,0,1] neg_hi:[0,0,1]
	v_pk_fma_f32 v[52:53], v[104:105], v[52:53], v[62:63] op_sel_hi:[1,0,1]
	s_nop 0
	v_mov_b32_e32 v111, v53
	v_pk_add_f32 v[62:63], v[50:51], v[110:111]
	v_add_u32_e32 v51, 0x3000, v114
	v_cvt_pk_bf16_f32 v50, v62, v63
	ds_write2_b32 v51, v50, v61 offset0:64 offset1:132
	s_waitcnt lgkmcnt(0)
	v_add_u32_e32 v61, v79, v116
	ds_read_b128 v[50:53], v61 offset:12544
	ds_read_b128 v[110:113], v61 offset:12608
	s_waitcnt lgkmcnt(1)
	v_mfma_f32_16x16x32_bf16 v[50:53], v[50:53], v[34:37], 0
	ds_read_b128 v[128:131], v61 offset:12672
	s_waitcnt lgkmcnt(1)
	v_mfma_f32_16x16x32_bf16 v[50:53], v[110:113], v[38:41], v[50:53]
	ds_read_b128 v[110:113], v61 offset:12736
	s_waitcnt lgkmcnt(0)
	s_waitcnt vmcnt(3)
	v_lshlrev_b32_e32 v60, 16, v60
	s_waitcnt vmcnt(2)
	v_lshlrev_b32_e32 v61, 16, v58
	s_waitcnt lgkmcnt(1)
	v_mfma_f32_16x16x32_bf16 v[50:53], v[128:131], v[42:45], v[50:53]
	s_waitcnt vmcnt(1)
	v_lshlrev_b32_e32 v58, 16, v59
	s_waitcnt vmcnt(0)
	v_lshlrev_b32_e32 v59, 16, v65
	s_waitcnt lgkmcnt(0)
	v_mfma_f32_16x16x32_bf16 v[50:53], v[110:113], v[46:49], v[50:53]

; __device__ __forceinline__ void resnorm_rows(const float* hin, const bf16_t* tmp, const float* g1, float* hout, const float* g2, bf16_t* xn, int gw, int NGW, int lane) {
;     for (int row = gw; row < NTOK; row += NGW) {
;         const u32x2* tr = (const u32x2*)(tmp + (size_t)row * DMODEL) + lane; f32x4 t[4]; float ss = 0.f;
; #pragma unroll
;         for (int j = 0; j < 4; ++j) { const u32x2 w = __builtin_nontemporal_load(tr + 64 * j); t[j] = (f32x4){bflo(w.x), bfhi(w.x), bflo(w.y), bfhi(w.y)}; ss += (t[j][0] * t[j][0] + t[j][1] * t[j][1]) + (t[j][2] * t[j][2] + t[j][3] * t[j][3]); }
;         const float rs = __builtin_amdgcn_rsqf(wave_sum(ss) * (1.f / DMODEL) + EPSN);
;         const f32x4* hr = (const f32x4*)(hin + (size_t)row * DMODEL) + lane; f32x4* ho = (f32x4*)(hout + (size_t)row * DMODEL) + lane; float s2 = 0.f;
; template <int ph> __device__ __forceinline__ void phase_body(LAS unsigned char* lds, int vcu, int NGW) {
;     ...
;                 resnorm_rows(li == 0 ? P->in[0] : P->out, tmp1, P->in[2] + li * 1024, P->out, P->in[3] + li * 1024, xn, gw, NGW, lane);
.LBB0_1116:
	s_cmp_lt_i32 s24, 8
	s_cselect_b64 s[4:5], -1, 0
	s_cmp_gt_i32 s25, 7
	s_cselect_b64 s[6:7], -1, 0
	s_and_b64 s[4:5], s[4:5], s[6:7]
	s_andn2_b64 vcc, exec, s[4:5]
	s_cbranch_vccnz .LBB0_1190
	s_mov_b64 s[4:5], s[0:1]
	v_mov_b32_e32 v2, v1
	s_lshl_b32 s17, s33, 3
	v_readfirstlane_b32 s3, v2
	s_ashr_i32 s16, s3, 6
	s_add_i32 s3, s16, s17
	s_cmpk_gt_i32 s3, 0x3fff
	s_cbranch_scc1 .LBB0_1122
	v_and_b32_e32 v4, 63, v2
	v_mbcnt_lo_u32_b32 v2, -1, 0
	v_mbcnt_hi_u32_b32 v2, -1, v2
	v_and_b32_e32 v3, 64, v2
	v_add_u32_e32 v3, 64, v3
	v_xor_b32_e32 v5, 1, v2
	v_cmp_lt_i32_e32 vcc, v5, v3
	s_load_dwordx4 s[8:11], s[4:5], 0x110
	s_load_dwordx2 s[6:7], s[4:5], 0x0
	s_load_dwordx4 s[20:23], s[4:5], 0x10
	v_cndmask_b32_e32 v5, v2, v5, vcc
	s_waitcnt lgkmcnt(0)
	v_lshlrev_b32_e32 v26, 2, v5
	v_xor_b32_e32 v5, 2, v2
	v_cmp_lt_i32_e32 vcc, v5, v3
	s_cmp_lg_u64 s[22:23], 0
	s_cselect_b64 s[4:5], -1, 0
	v_cndmask_b32_e32 v5, v2, v5, vcc
	v_lshlrev_b32_e32 v27, 2, v5
	v_xor_b32_e32 v5, 4, v2
	v_cmp_lt_i32_e32 vcc, v5, v3
	s_ashr_i32 s18, s16, 31
	s_ashr_i32 s19, s17, 31
	v_cndmask_b32_e32 v5, v2, v5, vcc
	v_lshlrev_b32_e32 v28, 2, v5
	v_xor_b32_e32 v5, 8, v2
	v_cmp_lt_i32_e32 vcc, v5, v3
	s_add_u32 s16, s16, s17
	s_addc_u32 s17, s18, s19
	v_cndmask_b32_e32 v5, v2, v5, vcc
	v_lshlrev_b32_e32 v29, 2, v5
	v_xor_b32_e32 v5, 16, v2
	v_cmp_lt_i32_e32 vcc, v5, v3
	s_lshl_b64 s[18:19], s[16:17], 11
	s_add_u32 s10, s10, s18
	v_cndmask_b32_e32 v5, v2, v5, vcc
	v_lshlrev_b32_e32 v30, 2, v5
	v_xor_b32_e32 v5, 32, v2
	v_cmp_lt_i32_e32 vcc, v5, v3
	v_mov_b32_e32 v3, 0
	s_addc_u32 s11, s11, s19
	v_cndmask_b32_e32 v2, v2, v5, vcc
	v_lshlrev_b32_e32 v31, 2, v2
	v_lshlrev_b32_e32 v2, 4, v4
	v_lshlrev_b32_e32 v4, 3, v4
	v_mov_b32_e32 v5, v3
	s_lshl_b64 s[16:17], s[16:17], 12
	v_lshl_add_u64 v[14:15], s[20:21], 0, v[2:3]
	v_lshl_add_u64 v[16:17], s[22:23], 0, v[2:3]
	v_lshl_add_u64 v[4:5], s[10:11], 0, v[4:5]
	s_mov_b64 s[10:11], 0x9d00600
	s_ashr_i32 s27, s26, 31
	v_or_b32_e32 v20, s16, v2
	v_cndmask_b32_e64 v2, 0, 1, s[4:5]
	v_lshl_add_u64 v[18:19], v[4:5], 0, s[10:11]
	s_lshl_b64 s[10:11], s[26:27], 11
	v_mov_b32_e32 v21, s17
	s_lshl_b64 s[16:17], s[26:27], 12
	s_mov_b64 s[18:19], 0x400
	s_mov_b64 s[20:21], 0x800
	v_mov_b32_e32 v32, 0x358637bd
	s_mov_b64 s[22:23], 0xc00
	v_cmp_ne_u32_e64 s[4:5], 1, v2
	s_mov_b32 s97, 0
	s_branch .LBB0_1120

; __device__ __forceinline__ void st16_wt(void* p, u32x4 v) { asm volatile("global_store_dwordx4 %0, %1, off sc1\n\ts_nop 4" :: "v"(p), "v"(v) : "memory"); }
; __device__ __forceinline__ void resnorm_rows(const float* hin, const bf16_t* tmp, const float* g1, float* hout, const float* g2, bf16_t* xn, int gw, int NGW, int lane) {
;     for (int row = gw; row < NTOK; row += NGW) {
;         const u32x2* tr = (const u32x2*)(tmp + (size_t)row * DMODEL) + lane; f32x4 t[4]; float ss = 0.f;
; #pragma unroll
;         for (int j = 0; j < 4; ++j) { const u32x2 w = __builtin_nontemporal_load(tr + 64 * j); t[j] = (f32x4){bflo(w.x), bfhi(w.x), bflo(w.y), bfhi(w.y)}; ss += (t[j][0] * t[j][0] + t[j][1] * t[j][1]) + (t[j][2] * t[j][2] + t[j][3] * t[j][3]); }
;         const float rs = __builtin_amdgcn_rsqf(wave_sum(ss) * (1.f / DMODEL) + EPSN);
;         const f32x4* hr = (const f32x4*)(hin + (size_t)row * DMODEL) + lane; f32x4* ho = (f32x4*)(hout + (size_t)row * DMODEL) + lane; float s2 = 0.f;
; #pragma unroll
;         for (int j = 0; j < 4; ++j) { const f32x4 gg = ((const f32x4*)g1)[lane + 64 * j]; f32x4 h = __builtin_nontemporal_load(hr + 64 * j);
;             h[0] += t[j][0] * rs * gg[0]; h[1] += t[j][1] * rs * gg[1]; h[2] += t[j][2] * rs * gg[2]; h[3] += t[j][3] * rs * gg[3];
;             st16_wt(ho + 64 * j, __builtin_bit_cast(u32x4, h)); t[j] = h; s2 += (h[0] * h[0] + h[1] * h[1]) + (h[2] * h[2] + h[3] * h[3]); }
.LBB0_1120:
	v_add_co_u32_e32 v2, vcc, 0xf6300000, v18
	v_lshl_add_u64 v[38:39], s[6:7], 0, v[20:21]
	s_nop 0
	v_addc_co_u32_e32 v3, vcc, -1, v19, vcc
	s_cmp_lg_u32 s97, 0
	s_cbranch_scc0 .Lrn_first_ph7
	s_waitcnt vmcnt(8)
	s_branch .Lrn_go_ph7
.Lrn_first_ph7:
	s_mov_b32 s97, 1
	global_load_dwordx2 v[160:161], v[2:3], off offset:-1536 nt
	global_load_dwordx2 v[162:163], v[2:3], off offset:-1024 nt
	global_load_dwordx2 v[164:165], v[2:3], off offset:-512 nt
	global_load_dwordx2 v[166:167], v[2:3], off nt
	global_load_dwordx4 v[168:171], v[38:39], off nt
	global_load_dwordx4 v[172:175], v[38:39], off offset:1024 nt
	global_load_dwordx4 v[176:179], v[38:39], off offset:2048 nt
	global_load_dwordx4 v[180:183], v[38:39], off offset:3072 nt
	global_load_dwordx4 v[200:203], v[14:15], off
	global_load_dwordx4 v[120:123], v[14:15], off offset:1024
	global_load_dwordx4 v[128:131], v[14:15], off offset:2048
	global_load_dwordx4 v[136:139], v[14:15], off offset:3072
	global_load_dwordx4 v[144:147], v[16:17], off
	global_load_dwordx4 v[148:151], v[16:17], off offset:1024
	global_load_dwordx4 v[152:155], v[16:17], off offset:2048
	global_load_dwordx4 v[156:159], v[16:17], off offset:3072
	s_waitcnt vmcnt(0)
.Lrn_go_ph7:
	v_lshl_add_u64 v[196:197], v[2:3], 0, s[10:11]
	v_lshl_add_u64 v[198:199], v[38:39], 0, s[16:17]
	v_mov_b64_e32 v[10:11], v[160:161]
	v_mov_b64_e32 v[12:13], v[162:163]
	v_mov_b64_e32 v[22:23], v[164:165]
	v_mov_b64_e32 v[24:25], v[166:167]
	v_mov_b64_e32 v[6:7], v[168:169]
	v_mov_b64_e32 v[8:9], v[170:171]
	v_mov_b64_e32 v[124:125], v[172:173]
	v_mov_b64_e32 v[126:127], v[174:175]
	v_mov_b64_e32 v[132:133], v[176:177]
	v_mov_b64_e32 v[134:135], v[178:179]
	v_mov_b64_e32 v[140:141], v[180:181]
	v_mov_b64_e32 v[142:143], v[182:183]
	v_mov_b64_e32 v[2:3], v[200:201]
	v_mov_b64_e32 v[4:5], v[202:203]
	s_nop 0
	s_and_b64 vcc, exec, s[4:5]
	s_add_i32 s98, s3, s26
	s_cmpk_lt_i32 s98, 0x4000
	s_cbranch_scc0 .Lrn_nopf_ph7
	global_load_dwordx2 v[160:161], v[196:197], off offset:-1536 nt
	global_load_dwordx2 v[162:163], v[196:197], off offset:-1024 nt
	global_load_dwordx2 v[164:165], v[196:197], off offset:-512 nt
	global_load_dwordx2 v[166:167], v[196:197], off nt
	global_load_dwordx4 v[168:171], v[198:199], off nt
	global_load_dwordx4 v[172:175], v[198:199], off offset:1024 nt
	global_load_dwordx4 v[176:179], v[198:199], off offset:2048 nt
	global_load_dwordx4 v[180:183], v[198:199], off offset:3072 nt
.Lrn_nopf_ph7:
	v_and_b32_e32 v35, 0xffff0000, v11
	v_and_b32_e32 v37, 0xffff0000, v10
	v_lshlrev_b32_e32 v34, 16, v11
	v_lshlrev_b32_e32 v36, 16, v10
	v_lshlrev_b32_e32 v41, 16, v13
	v_lshlrev_b32_e32 v40, 16, v12
	v_and_b32_e32 v43, 0xffff0000, v13
	v_and_b32_e32 v42, 0xffff0000, v12
	v_mov_b32_e32 v12, v37
	v_mov_b32_e32 v13, v35
	v_lshlrev_b32_e32 v44, 16, v23
	v_and_b32_e32 v45, 0xffff0000, v23
	v_lshlrev_b32_e32 v46, 16, v22
	v_and_b32_e32 v47, 0xffff0000, v22
	v_mov_b32_e32 v10, v36
	v_mov_b32_e32 v11, v34
	v_pk_mul_f32 v[22:23], v[42:43], v[42:43]
	v_pk_mul_f32 v[12:13], v[12:13], v[12:13]
	v_lshlrev_b32_e32 v48, 16, v25
	v_and_b32_e32 v49, 0xffff0000, v25
	v_lshlrev_b32_e32 v50, 16, v24
	v_and_b32_e32 v51, 0xffff0000, v24
	v_mul_f32_e32 v24, v45, v45
	v_mul_f32_e32 v52, v47, v47
	v_pk_fma_f32 v[22:23], v[40:41], v[40:41], v[22:23]
	v_pk_fma_f32 v[10:11], v[10:11], v[10:11], v[12:13]
	v_pk_mul_f32 v[54:55], v[48:49], v[48:49]
	v_pk_mul_f32 v[56:57], v[50:51], v[50:51]
	v_pk_fma_f32 v[24:25], v[44:45], v[44:45], v[24:25] op_sel_hi:[1,1,0]
	v_pk_fma_f32 v[52:53], v[46:47], v[46:47], v[52:53] op_sel_hi:[1,1,0]
	v_pk_add_f32 v[12:13], v[22:23], v[22:23] op_sel:[0,1] op_sel_hi:[1,0]
	v_pk_add_f32 v[10:11], v[10:11], v[10:11] op_sel:[0,1] op_sel_hi:[1,0]
	v_mov_b32_e32 v53, v54
	v_mov_b32_e32 v25, v55
	v_mov_b32_e32 v13, v57
	v_mov_b32_e32 v11, v56
	v_pk_add_f32 v[22:23], v[52:53], v[24:25]
	v_pk_add_f32 v[10:11], v[10:11], v[12:13]
	v_lshl_add_u64 v[54:55], s[8:9], 0, v[20:21]
	v_pk_add_f32 v[10:11], v[10:11], v[22:23]
	s_nop 0
	v_add_f32_e32 v10, v10, v11
	ds_bpermute_b32 v11, v26, v10
	s_waitcnt lgkmcnt(0)
	v_add_f32_e32 v10, v10, v11
	ds_bpermute_b32 v11, v27, v10
	s_waitcnt lgkmcnt(0)
	v_add_f32_e32 v10, v10, v11
	ds_bpermute_b32 v11, v28, v10
	s_waitcnt lgkmcnt(0)
	v_add_f32_e32 v10, v10, v11
	ds_bpermute_b32 v11, v29, v10
	s_waitcnt lgkmcnt(0)
	v_add_f32_e32 v10, v10, v11
	ds_bpermute_b32 v11, v30, v10
	s_waitcnt lgkmcnt(0)
	v_add_f32_e32 v10, v10, v11
	ds_bpermute_b32 v11, v31, v10
	s_waitcnt lgkmcnt(0)
	v_add_f32_e32 v10, v10, v11
	v_fmamk_f32 v10, v10, 0x3a800000, v32
	v_rsq_f32_e32 v52, v10
	s_nop 0
	v_pk_mul_f32 v[10:11], v[52:53], v[36:37] op_sel_hi:[0,1]
	v_pk_mul_f32 v[12:13], v[52:53], v[34:35] op_sel_hi:[0,1]
	v_pk_fma_f32 v[2:3], v[2:3], v[10:11], v[6:7]
	v_pk_fma_f32 v[4:5], v[4:5], v[12:13], v[8:9]
	v_pk_mul_f32 v[22:23], v[52:53], v[40:41] op_sel_hi:[0,1]
	global_store_dwordx4 v[54:55], v[2:5], off sc1
	s_nop 4
	v_mov_b64_e32 v[6:7], v[120:121]
	v_mov_b64_e32 v[8:9], v[122:123]
	v_mov_b64_e32 v[10:11], v[124:125]
	v_mov_b64_e32 v[12:13], v[126:127]
	v_pk_mul_f32 v[36:37], v[52:53], v[42:43] op_sel_hi:[0,1]
	v_lshl_add_u64 v[34:35], v[54:55], 0, s[18:19]
	v_pk_mul_f32 v[42:43], v[52:53], v[48:49] op_sel_hi:[0,1]
	s_waitcnt vmcnt(1)
	v_mov_b32_e32 v24, v6
	v_mov_b32_e32 v25, v8
	v_mov_b32_e32 v40, v10
	v_mov_b32_e32 v41, v12
	v_mov_b32_e32 v8, v7
	v_mov_b32_e32 v12, v11
	v_pk_fma_f32 v[24:25], v[24:25], v[22:23], v[40:41]
	v_pk_fma_f32 v[22:23], v[8:9], v[36:37], v[12:13]
	v_mov_b32_e32 v6, v24
	v_mov_b32_e32 v7, v22
	v_mov_b32_e32 v8, v25
	v_mov_b32_e32 v9, v23
	global_store_dwordx4 v[34:35], v[6:9], off sc1
	s_nop 4
	v_mov_b64_e32 v[6:7], v[128:129]
	v_mov_b64_e32 v[8:9], v[130:131]
	v_mov_b64_e32 v[10:11], v[132:133]
	v_mov_b64_e32 v[12:13], v[134:135]
	v_pk_mul_f32 v[36:37], v[52:53], v[46:47] op_sel_hi:[0,1]
	v_pk_mul_f32 v[40:41], v[52:53], v[44:45] op_sel_hi:[0,1]
	v_lshl_add_u64 v[34:35], v[54:55], 0, s[20:21]
	v_pk_fma_f32 v[6:7], v[6:7], v[36:37], v[10:11]
	v_pk_fma_f32 v[8:9], v[8:9], v[40:41], v[12:13]
	v_pk_mul_f32 v[40:41], v[52:53], v[50:51] op_sel_hi:[0,1]
	global_store_dwordx4 v[34:35], v[6:9], off sc1
	s_nop 4
	v_mov_b64_e32 v[10:11], v[136:137]
	v_mov_b64_e32 v[12:13], v[138:139]
	v_mov_b64_e32 v[34:35], v[140:141]
	v_mov_b64_e32 v[36:37], v[142:143]
	v_lshl_add_u64 v[38:39], v[54:55], 0, s[22:23]
	v_pk_fma_f32 v[10:11], v[40:41], v[10:11], v[34:35]
	v_pk_fma_f32 v[12:13], v[42:43], v[12:13], v[36:37]
	s_nop 0
	global_store_dwordx4 v[38:39], v[10:13], off sc1
	s_nop 4
	s_cbranch_vccnz .LBB0_1119
; __device__ __forceinline__ unsigned cvtpk(float lo, float hi) { typedef __bf16 bf2 __attribute__((ext_vector_type(2))); f32x2 v = {lo, hi}; bf2 b = __builtin_convertvector(v, bf2); return __builtin_bit_cast(unsigned, b); }
; __device__ __forceinline__ void resnorm_rows(const float* hin, const bf16_t* tmp, const float* g1, float* hout, const float* g2, bf16_t* xn, int gw, int NGW, int lane) {
;     ...
;         if (g2) {
;             const float r2 = __builtin_amdgcn_rsqf(wave_sum(s2) * (1.f / DMODEL) + EPSN);
;             u32x2* o = (u32x2*)(xn + (size_t)row * DMODEL) + lane;
; #pragma unroll
;             for (int j = 0; j < 4; ++j) { const f32x4 gg = ((const f32x4*)g2)[lane + 64 * j]; u32x2 w; w.x = cvtpk(t[j][0] * r2 * gg[0], t[j][1] * r2 * gg[1]); w.y = cvtpk(t[j][2] * r2 * gg[2], t[j][3] * r2 * gg[3]); o[64 * j] = w; }
;         }
	v_mov_b64_e32 v[34:35], v[144:145]
	v_mov_b64_e32 v[36:37], v[146:147]
	v_mov_b32_e32 v40, v3
	v_mov_b32_e32 v41, v5
	v_mov_b32_e32 v38, v2
	v_mov_b32_e32 v39, v4
	v_pk_mul_f32 v[42:43], v[22:23], v[22:23]
	v_pk_mul_f32 v[40:41], v[40:41], v[40:41]
	v_mul_f32_e32 v44, v8, v8
	v_mul_f32_e32 v50, v6, v6
	v_pk_fma_f32 v[42:43], v[24:25], v[24:25], v[42:43]
	v_pk_fma_f32 v[38:39], v[38:39], v[38:39], v[40:41]
	v_pk_mul_f32 v[46:47], v[10:11], v[10:11]
	v_pk_mul_f32 v[48:49], v[12:13], v[12:13]
	v_pk_fma_f32 v[44:45], v[8:9], v[8:9], v[44:45] op_sel_hi:[1,1,0]
	v_pk_fma_f32 v[50:51], v[6:7], v[6:7], v[50:51] op_sel_hi:[1,1,0]
	v_pk_add_f32 v[40:41], v[42:43], v[42:43] op_sel_hi:[0,1]
	v_pk_add_f32 v[38:39], v[38:39], v[38:39] op_sel_hi:[0,1]
	v_mov_b32_e32 v50, v46
	v_mov_b32_e32 v44, v47
	v_mov_b32_e32 v40, v49
	v_mov_b32_e32 v38, v48
	v_pk_add_f32 v[42:43], v[50:51], v[44:45]
	v_pk_add_f32 v[38:39], v[38:39], v[40:41]
	s_nop 0
	v_pk_add_f32 v[38:39], v[42:43], v[38:39]
	s_nop 0
	v_add_f32_e32 v33, v38, v39
	ds_bpermute_b32 v38, v26, v33
	s_waitcnt lgkmcnt(0)
	v_add_f32_e32 v33, v33, v38
	ds_bpermute_b32 v38, v27, v33
	s_waitcnt lgkmcnt(0)
	v_add_f32_e32 v33, v33, v38
	ds_bpermute_b32 v38, v28, v33
	s_waitcnt lgkmcnt(0)
	v_add_f32_e32 v33, v33, v38
	ds_bpermute_b32 v38, v29, v33
	s_waitcnt lgkmcnt(0)
	v_add_f32_e32 v33, v33, v38
	ds_bpermute_b32 v38, v30, v33
	s_waitcnt lgkmcnt(0)
	v_add_f32_e32 v33, v33, v38
	ds_bpermute_b32 v38, v31, v33
	s_waitcnt lgkmcnt(0)
	v_add_f32_e32 v33, v33, v38
	v_fmamk_f32 v33, v33, 0x3a800000, v32
	v_rsq_f32_e32 v38, v33
	s_nop 0
	v_pk_mul_f32 v[2:3], v[2:3], v[38:39] op_sel_hi:[1,0]
	v_pk_mul_f32 v[4:5], v[4:5], v[38:39] op_sel_hi:[1,0]
	v_pk_mul_f32 v[6:7], v[6:7], v[38:39] op_sel_hi:[1,0]
	v_pk_mul_f32 v[8:9], v[8:9], v[38:39] op_sel_hi:[1,0]
	v_pk_mul_f32 v[2:3], v[34:35], v[2:3]
	v_pk_mul_f32 v[4:5], v[36:37], v[4:5]
	v_cvt_pk_bf16_f32 v2, v2, v3
	v_cvt_pk_bf16_f32 v3, v4, v5
	global_store_dwordx2 v[18:19], v[2:3], off offset:-1536
	v_mov_b64_e32 v[2:3], v[148:149]
	v_mov_b64_e32 v[4:5], v[150:151]
	v_mov_b32_e32 v34, v24
	v_mov_b32_e32 v35, v22
	v_mov_b32_e32 v22, v25
	v_pk_mul_f32 v[24:25], v[34:35], v[38:39] op_sel_hi:[1,0]
	v_pk_mul_f32 v[22:23], v[22:23], v[38:39] op_sel_hi:[1,0]
	v_pk_mul_f32 v[2:3], v[2:3], v[24:25]
	v_pk_mul_f32 v[4:5], v[4:5], v[22:23]
	v_cvt_pk_bf16_f32 v2, v2, v3
	v_cvt_pk_bf16_f32 v3, v4, v5
	global_store_dwordx2 v[18:19], v[2:3], off offset:-1024
	v_mov_b64_e32 v[2:3], v[152:153]
	v_mov_b64_e32 v[4:5], v[154:155]
	v_pk_mul_f32 v[2:3], v[6:7], v[2:3]
	v_pk_mul_f32 v[4:5], v[8:9], v[4:5]
	v_cvt_pk_bf16_f32 v2, v2, v3
	v_cvt_pk_bf16_f32 v3, v4, v5
	global_store_dwordx2 v[18:19], v[2:3], off offset:-512
	v_mov_b64_e32 v[2:3], v[156:157]
	v_mov_b64_e32 v[4:5], v[158:159]
	v_pk_mul_f32 v[6:7], v[10:11], v[38:39] op_sel_hi:[1,0]
	v_pk_mul_f32 v[8:9], v[12:13], v[38:39] op_sel_hi:[1,0]
	v_pk_mul_f32 v[2:3], v[6:7], v[2:3]
	v_pk_mul_f32 v[4:5], v[8:9], v[4:5]
	v_cvt_pk_bf16_f32 v2, v2, v3
	v_cvt_pk_bf16_f32 v3, v4, v5
	global_store_dwordx2 v[18:19], v[2:3], off
	s_branch .LBB0_1119

; __device__ __forceinline__ void resnorm_rows(const float* hin, const bf16_t* tmp, const float* g1, float* hout, const float* g2, bf16_t* xn, int gw, int NGW, int lane) {
;     for (int row = gw; row < NTOK; row += NGW) {
;         const u32x2* tr = (const u32x2*)(tmp + (size_t)row * DMODEL) + lane; f32x4 t[4]; float ss = 0.f;
; #pragma unroll
;         for (int j = 0; j < 4; ++j) { const u32x2 w = __builtin_nontemporal_load(tr + 64 * j); t[j] = (f32x4){bflo(w.x), bfhi(w.x), bflo(w.y), bfhi(w.y)}; ss += (t[j][0] * t[j][0] + t[j][1] * t[j][1]) + (t[j][2] * t[j][2] + t[j][3] * t[j][3]); }
;         const float rs = __builtin_amdgcn_rsqf(wave_sum(ss) * (1.f / DMODEL) + EPSN);
;         const f32x4* hr = (const f32x4*)(hin + (size_t)row * DMODEL) + lane; f32x4* ho = (f32x4*)(hout + (size_t)row * DMODEL) + lane; float s2 = 0.f;
; #pragma unroll
;         for (int j = 0; j < 4; ++j) { const f32x4 gg = ((const f32x4*)g1)[lane + 64 * j]; f32x4 h = __builtin_nontemporal_load(hr + 64 * j);
; template <int ph> __device__ __forceinline__ void phase_body(LAS unsigned char* lds, int vcu, int NGW) {
;     ...
;                 resnorm_rows(P->out, tmp2, P->in[4] + li * 1024, P->out, last ? nullptr : P->in[1] + (li + 1) * 1024, xn, gw, NGW, lane);
.LBB0_1438:
	s_cmp_lt_i32 s24, 11
	s_cselect_b64 s[4:5], -1, 0
	s_cmp_gt_i32 s25, 10
	s_cselect_b64 s[6:7], -1, 0
	s_and_b64 s[4:5], s[4:5], s[6:7]
	s_andn2_b64 vcc, exec, s[4:5]
	s_cbranch_vccnz .LBB0_1564
	s_mov_b64 s[6:7], s[0:1]
	s_load_dwordx2 s[4:5], s[6:7], 0x118
	s_waitcnt lgkmcnt(0)
	v_mov_b32_e32 v18, v1
	s_lshl_b32 s8, s33, 3
	v_readfirstlane_b32 s3, v18
	s_ashr_i32 s22, s3, 6
	v_and_b32_e32 v34, 63, v18
	s_add_i32 s3, s22, s8
	s_cmpk_gt_i32 s3, 0x3fff
	v_lshlrev_b32_e32 v4, 3, v34
	s_cbranch_scc1 .LBB0_1442
	v_mbcnt_lo_u32_b32 v2, -1, 0
	v_mbcnt_hi_u32_b32 v2, -1, v2
	v_and_b32_e32 v3, 64, v2
	v_add_u32_e32 v3, 64, v3
	v_xor_b32_e32 v5, 1, v2
	v_cmp_lt_i32_e32 vcc, v5, v3
	s_load_dwordx2 s[10:11], s[6:7], 0x8
	s_load_dwordx2 s[16:17], s[6:7], 0x20
	s_load_dwordx2 s[18:19], s[6:7], 0x110
	v_cndmask_b32_e32 v5, v2, v5, vcc
	v_lshlrev_b32_e32 v19, 2, v5
	v_xor_b32_e32 v5, 2, v2
	v_cmp_lt_i32_e32 vcc, v5, v3
	s_waitcnt lgkmcnt(0)
	s_add_u32 s10, s10, 0x1000
	v_lshlrev_b32_e32 v16, 4, v34
	v_cndmask_b32_e32 v5, v2, v5, vcc
	v_lshlrev_b32_e32 v20, 2, v5
	v_xor_b32_e32 v5, 4, v2
	v_cmp_lt_i32_e32 vcc, v5, v3
	v_mov_b32_e32 v17, 0
	s_addc_u32 s11, s11, 0
	v_cndmask_b32_e32 v5, v2, v5, vcc
	v_lshlrev_b32_e32 v21, 2, v5
	v_xor_b32_e32 v5, 8, v2
	v_cmp_lt_i32_e32 vcc, v5, v3
	v_or_b32_e32 v8, 0x400, v16
	v_mov_b32_e32 v9, v17
	v_cndmask_b32_e32 v5, v2, v5, vcc
	v_or_b32_e32 v10, 0x800, v16
	v_mov_b32_e32 v11, v17
	v_or_b32_e32 v12, 0xc00, v16
	v_mov_b32_e32 v13, v17
	v_lshlrev_b32_e32 v22, 2, v5
	v_xor_b32_e32 v5, 16, v2
	v_lshl_add_u64 v[6:7], s[10:11], 0, v[16:17]
	v_lshl_add_u64 v[8:9], s[10:11], 0, v[8:9]
	v_lshl_add_u64 v[10:11], s[10:11], 0, v[10:11]
	v_lshl_add_u64 v[12:13], s[10:11], 0, v[12:13]
	s_ashr_i32 s9, s22, 31
	s_ashr_i32 s11, s8, 31
	v_cmp_lt_i32_e32 vcc, v5, v3
	s_add_u32 s10, s22, s8
	s_addc_u32 s11, s9, s11
	v_cndmask_b32_e32 v5, v2, v5, vcc
	v_lshlrev_b32_e32 v23, 2, v5
	v_xor_b32_e32 v5, 32, v2
	s_lshl_b64 s[8:9], s[10:11], 11
	v_cmp_lt_i32_e32 vcc, v5, v3
	s_add_u32 s8, s4, s8
	s_addc_u32 s9, s5, s9
	v_cndmask_b32_e32 v2, v2, v5, vcc
	v_mov_b32_e32 v5, v17
	v_lshl_add_u64 v[14:15], s[8:9], 0, v[4:5]
	s_mov_b64 s[8:9], 0x9d00400
	s_ashr_i32 s27, s26, 31
	v_lshl_add_u64 v[14:15], v[14:15], 0, s[8:9]
	s_lshl_b64 s[8:9], s[26:27], 11
	s_lshl_b64 s[10:11], s[10:11], 12
	s_add_u32 s10, s18, s10
	s_addc_u32 s11, s19, s11
	v_lshlrev_b32_e32 v24, 2, v2
	v_lshl_add_u64 v[2:3], s[16:17], 0, v[16:17]
	v_lshl_add_u64 v[16:17], s[10:11], 0, v[16:17]
	s_lshl_b64 s[10:11], s[26:27], 12
	s_mov_b64 s[16:17], 0x400
	s_mov_b64 s[18:19], 0x800
	s_mov_b64 s[20:21], 0xc00
	v_mov_b32_e32 v5, 0x358637bd
	s_mov_b32 s23, s3
	s_mov_b32 s97, 0
.LBB0_1441:
	s_cmp_lg_u32 s97, 0
	s_cbranch_scc0 .Lrn_first_ph10
	s_waitcnt vmcnt(8)
	s_branch .Lrn_go_ph10
.Lrn_first_ph10:
	s_mov_b32 s97, 1
	global_load_dwordx2 v[160:161], v[14:15], off offset:-512 nt
	global_load_dwordx2 v[162:163], v[14:15], off nt
	global_load_dwordx2 v[164:165], v[14:15], off offset:-1024 nt
	global_load_dwordx2 v[166:167], v[14:15], off offset:512 nt
	global_load_dwordx4 v[168:171], v[16:17], off nt
	global_load_dwordx4 v[172:175], v[16:17], off offset:1024 nt
	global_load_dwordx4 v[176:179], v[16:17], off offset:2048 nt
	global_load_dwordx4 v[180:183], v[16:17], off offset:3072 nt
	global_load_dwordx4 v[200:203], v[2:3], off
	global_load_dwordx4 v[120:123], v[2:3], off offset:1024
	global_load_dwordx4 v[128:131], v[2:3], off offset:2048
	global_load_dwordx4 v[136:139], v[2:3], off offset:3072
	global_load_dwordx4 v[144:147], v[6:7], off
	global_load_dwordx4 v[148:151], v[8:9], off
	global_load_dwordx4 v[152:155], v[10:11], off
	global_load_dwordx4 v[156:159], v[12:13], off
	s_waitcnt vmcnt(0)
.Lrn_go_ph10:
	v_lshl_add_u64 v[196:197], v[14:15], 0, s[8:9]
	v_lshl_add_u64 v[198:199], v[16:17], 0, s[10:11]
	v_mov_b64_e32 v[36:37], v[160:161]
	v_mov_b64_e32 v[38:39], v[162:163]
	v_mov_b64_e32 v[40:41], v[164:165]
	v_mov_b64_e32 v[42:43], v[166:167]
	v_mov_b64_e32 v[30:31], v[168:169]
	v_mov_b64_e32 v[32:33], v[170:171]
	v_mov_b64_e32 v[124:125], v[172:173]
	v_mov_b64_e32 v[126:127], v[174:175]
	v_mov_b64_e32 v[132:133], v[176:177]
	v_mov_b64_e32 v[134:135], v[178:179]
	v_mov_b64_e32 v[140:141], v[180:181]
	v_mov_b64_e32 v[142:143], v[182:183]
	v_mov_b64_e32 v[26:27], v[200:201]
	v_mov_b64_e32 v[28:29], v[202:203]
	s_add_i32 s23, s23, s26
	s_cmpk_lt_i32 s23, 0x4000
	s_cbranch_scc0 .Lrn_nopf_ph10
	global_load_dwordx2 v[160:161], v[196:197], off offset:-512 nt
	global_load_dwordx2 v[162:163], v[196:197], off nt
	global_load_dwordx2 v[164:165], v[196:197], off offset:-1024 nt
	global_load_dwordx2 v[166:167], v[196:197], off offset:512 nt
	global_load_dwordx4 v[168:171], v[198:199], off nt
	global_load_dwordx4 v[172:175], v[198:199], off offset:1024 nt
	global_load_dwordx4 v[176:179], v[198:199], off offset:2048 nt
	global_load_dwordx4 v[180:183], v[198:199], off offset:3072 nt
; __device__ __forceinline__ void resnorm_rows(const float* hin, const bf16_t* tmp, const float* g1, float* hout, const float* g2, bf16_t* xn, int gw, int NGW, int lane) {
;     for (int row = gw; row < NTOK; row += NGW) {
;         const u32x2* tr = (const u32x2*)(tmp + (size_t)row * DMODEL) + lane; f32x4 t[4]; float ss = 0.f;
; #pragma unroll
;         for (int j = 0; j < 4; ++j) { const u32x2 w = __builtin_nontemporal_load(tr + 64 * j); t[j] = (f32x4){bflo(w.x), bfhi(w.x), bflo(w.y), bfhi(w.y)}; ss += (t[j][0] * t[j][0] + t[j][1] * t[j][1]) + (t[j][2] * t[j][2] + t[j][3] * t[j][3]); }
;         const float rs = __builtin_amdgcn_rsqf(wave_sum(ss) * (1.f / DMODEL) + EPSN);
.Lrn_nopf_ph10:
	v_lshlrev_b32_e32 v45, 16, v37
	v_and_b32_e32 v47, 0xffff0000, v37
	v_and_b32_e32 v46, 0xffff0000, v36
	v_lshlrev_b32_e32 v50, 16, v39
	v_and_b32_e32 v51, 0xffff0000, v39
	v_and_b32_e32 v37, 0xffff0000, v40
	v_and_b32_e32 v39, 0xffff0000, v41
	v_lshlrev_b32_e32 v44, 16, v36
	v_lshlrev_b32_e32 v48, 16, v38
	v_and_b32_e32 v49, 0xffff0000, v38
	v_lshlrev_b32_e32 v36, 16, v40
	v_lshlrev_b32_e32 v38, 16, v41
	v_pk_mul_f32 v[40:41], v[46:47], v[46:47]
	v_mul_f32_e32 v60, v37, v37
	v_mul_f32_e32 v62, v39, v39
	v_lshlrev_b32_e32 v52, 16, v42
	v_and_b32_e32 v55, 0xffff0000, v42
	v_and_b32_e32 v54, s0, v42
	v_lshlrev_b32_e32 v56, 16, v43
	v_and_b32_e32 v57, 0xffff0000, v43
	v_mul_f32_e32 v42, v49, v49
	v_mul_f32_e32 v58, v51, v51
	v_pk_fma_f32 v[40:41], v[44:45], v[44:45], v[40:41]
	v_pk_fma_f32 v[60:61], v[36:37], v[36:37], v[60:61] op_sel_hi:[1,1,0]
	v_pk_fma_f32 v[62:63], v[38:39], v[38:39], v[62:63] op_sel_hi:[1,1,0]
	v_pk_mul_f32 v[64:65], v[54:55], v[54:55]
	v_pk_mul_f32 v[66:67], v[56:57], v[56:57]
	v_pk_fma_f32 v[42:43], v[48:49], v[48:49], v[42:43] op_sel_hi:[1,1,0]
	v_pk_fma_f32 v[58:59], v[50:51], v[50:51], v[58:59] op_sel_hi:[1,1,0]
	v_pk_add_f32 v[40:41], v[40:41], v[40:41] op_sel:[0,1] op_sel_hi:[1,0]
	v_pk_add_f32 v[60:61], v[60:61], v[62:63]
	v_mov_b32_e32 v43, v66
	v_mov_b32_e32 v59, v67
	v_mul_f32_e32 v61, v52, v52
	v_mov_b32_e32 v41, v65
	v_pk_add_f32 v[42:43], v[42:43], v[58:59]
	v_pk_add_f32 v[40:41], v[60:61], v[40:41]
	v_mov_b32_e32 v53, v55
	v_pk_add_f32 v[40:41], v[40:41], v[42:43]
	v_mov_b32_e32 v42, v44
	v_add_f32_e32 v25, v40, v41
	ds_bpermute_b32 v35, v19, v25
	v_mov_b32_e32 v43, v46
	v_mov_b32_e32 v46, v45
	v_lshl_add_u64 v[40:41], v[16:17], 0, s[16:17]
	s_waitcnt lgkmcnt(0)
	v_add_f32_e32 v25, v25, v35
	ds_bpermute_b32 v35, v20, v25
	s_waitcnt lgkmcnt(0)
	v_add_f32_e32 v25, v25, v35
	ds_bpermute_b32 v35, v21, v25
	s_waitcnt lgkmcnt(0)
	v_add_f32_e32 v25, v25, v35
	ds_bpermute_b32 v35, v22, v25
	s_waitcnt lgkmcnt(0)
	v_add_f32_e32 v25, v25, v35
	ds_bpermute_b32 v35, v23, v25
	s_waitcnt lgkmcnt(0)
	v_add_f32_e32 v25, v25, v35
	ds_bpermute_b32 v35, v24, v25
	s_waitcnt lgkmcnt(0)
; __device__ __forceinline__ unsigned cvtpk(float lo, float hi) { typedef __bf16 bf2 __attribute__((ext_vector_type(2))); f32x2 v = {lo, hi}; bf2 b = __builtin_convertvector(v, bf2); return __builtin_bit_cast(unsigned, b); }
; __device__ __forceinline__ void st16_wt(void* p, u32x4 v) { asm volatile("global_store_dwordx4 %0, %1, off sc1\n\ts_nop 4" :: "v"(p), "v"(v) : "memory"); }
; __device__ __forceinline__ void resnorm_rows(const float* hin, const bf16_t* tmp, const float* g1, float* hout, const float* g2, bf16_t* xn, int gw, int NGW, int lane) {
;     ...
;         const f32x4* hr = (const f32x4*)(hin + (size_t)row * DMODEL) + lane; f32x4* ho = (f32x4*)(hout + (size_t)row * DMODEL) + lane; float s2 = 0.f;
; #pragma unroll
;         for (int j = 0; j < 4; ++j) { const f32x4 gg = ((const f32x4*)g1)[lane + 64 * j]; f32x4 h = __builtin_nontemporal_load(hr + 64 * j);
;             h[0] += t[j][0] * rs * gg[0]; h[1] += t[j][1] * rs * gg[1]; h[2] += t[j][2] * rs * gg[2]; h[3] += t[j][3] * rs * gg[3];
;             st16_wt(ho + 64 * j, __builtin_bit_cast(u32x4, h)); t[j] = h; s2 += (h[0] * h[0] + h[1] * h[1]) + (h[2] * h[2] + h[3] * h[3]); }
;         if (g2) {
;             const float r2 = __builtin_amdgcn_rsqf(wave_sum(s2) * (1.f / DMODEL) + EPSN);
;             u32x2* o = (u32x2*)(xn + (size_t)row * DMODEL) + lane;
; #pragma unroll
;             for (int j = 0; j < 4; ++j) { const f32x4 gg = ((const f32x4*)g2)[lane + 64 * j]; u32x2 w; w.x = cvtpk(t[j][0] * r2 * gg[0], t[j][1] * r2 * gg[1]); w.y = cvtpk(t[j][2] * r2 * gg[2], t[j][3] * r2 * gg[3]); o[64 * j] = w; }
;         }
	v_add_f32_e32 v25, v25, v35
	v_fmamk_f32 v25, v25, 0x3a800000, v5
	v_rsq_f32_e32 v54, v25
	s_nop 0
	v_pk_mul_f32 v[36:37], v[54:55], v[36:37] op_sel_hi:[0,1]
	v_pk_mul_f32 v[38:39], v[54:55], v[38:39] op_sel_hi:[0,1]
	v_pk_fma_f32 v[26:27], v[26:27], v[36:37], v[30:31]
	v_pk_fma_f32 v[28:29], v[28:29], v[38:39], v[32:33]
	v_pk_mul_f32 v[42:43], v[54:55], v[42:43] op_sel_hi:[0,1]
	global_store_dwordx4 v[16:17], v[26:29], off sc1
	s_nop 4
	v_mov_b64_e32 v[30:31], v[120:121]
	v_mov_b64_e32 v[32:33], v[122:123]
	v_mov_b64_e32 v[36:37], v[124:125]
	v_mov_b64_e32 v[38:39], v[126:127]
	v_pk_mul_f32 v[44:45], v[54:55], v[46:47] op_sel_hi:[0,1]
	v_pk_mul_f32 v[46:47], v[54:55], v[48:49] op_sel_hi:[0,1]
	v_pk_mul_f32 v[48:49], v[54:55], v[50:51] op_sel_hi:[0,1]
	v_pk_mul_f32 v[50:51], v[54:55], v[52:53] op_sel_hi:[0,1]
	v_pk_mul_f32 v[52:53], v[54:55], v[56:57] op_sel_hi:[0,1]
	v_pk_fma_f32 v[30:31], v[30:31], v[42:43], v[36:37]
	v_pk_fma_f32 v[32:33], v[32:33], v[44:45], v[38:39]
	v_lshl_add_u64 v[44:45], v[16:17], 0, s[18:19]
	global_store_dwordx4 v[40:41], v[30:33], off sc1
	s_nop 4
	v_mov_b64_e32 v[36:37], v[128:129]
	v_mov_b64_e32 v[38:39], v[130:131]
	v_mov_b64_e32 v[40:41], v[132:133]
	v_mov_b64_e32 v[42:43], v[134:135]
	v_pk_fma_f32 v[36:37], v[36:37], v[46:47], v[40:41]
	v_pk_fma_f32 v[38:39], v[38:39], v[48:49], v[42:43]
	v_lshl_add_u64 v[48:49], v[16:17], 0, s[20:21]
	global_store_dwordx4 v[44:45], v[36:39], off sc1
	s_nop 4
	v_mov_b64_e32 v[40:41], v[136:137]
	v_mov_b64_e32 v[42:43], v[138:139]
	v_mov_b64_e32 v[44:45], v[140:141]
	v_mov_b64_e32 v[46:47], v[142:143]
	v_lshl_add_u64 v[16:17], v[16:17], 0, s[10:11]
	v_pk_fma_f32 v[40:41], v[50:51], v[40:41], v[44:45]
	v_pk_fma_f32 v[42:43], v[52:53], v[42:43], v[46:47]
	v_mov_b32_e32 v50, v27
	global_store_dwordx4 v[48:49], v[40:43], off sc1
	s_nop 4
	v_mov_b64_e32 v[44:45], v[144:145]
	v_mov_b64_e32 v[46:47], v[146:147]
	v_mov_b32_e32 v51, v29
	v_mov_b32_e32 v48, v26
	v_mov_b32_e32 v49, v28
	v_pk_mul_f32 v[50:51], v[50:51], v[50:51]
	v_mov_b32_e32 v52, v31
	v_mov_b32_e32 v53, v33
	v_pk_fma_f32 v[48:49], v[48:49], v[48:49], v[50:51]
	v_mov_b32_e32 v50, v30
	v_mov_b32_e32 v51, v32
	v_pk_mul_f32 v[52:53], v[52:53], v[52:53]
	v_pk_add_f32 v[48:49], v[48:49], v[48:49] op_sel_hi:[0,1]
	v_pk_fma_f32 v[50:51], v[50:51], v[50:51], v[52:53]
	v_mul_f32_e32 v48, v36, v36
	v_pk_add_f32 v[50:51], v[50:51], v[50:51] op_sel_hi:[0,1]
	v_mul_f32_e32 v50, v38, v38
	v_pk_fma_f32 v[52:53], v[36:37], v[36:37], v[48:49] op_sel_hi:[1,1,0]
	v_pk_fma_f32 v[54:55], v[38:39], v[38:39], v[50:51] op_sel_hi:[1,1,0]
	v_pk_mul_f32 v[56:57], v[40:41], v[40:41]
	v_pk_mul_f32 v[58:59], v[42:43], v[42:43]
	v_mov_b32_e32 v52, v56
	v_mov_b32_e32 v54, v57
	v_mov_b32_e32 v48, v58
	v_mov_b32_e32 v50, v59
	v_pk_add_f32 v[52:53], v[52:53], v[54:55]
	v_pk_add_f32 v[48:49], v[48:49], v[50:51]
	s_nop 0
	v_pk_add_f32 v[48:49], v[52:53], v[48:49]
	s_nop 0
	v_add_f32_e32 v25, v48, v49
	ds_bpermute_b32 v35, v19, v25
	s_waitcnt lgkmcnt(0)
	v_add_f32_e32 v25, v25, v35
	ds_bpermute_b32 v35, v20, v25
	s_waitcnt lgkmcnt(0)
	v_add_f32_e32 v25, v25, v35
	ds_bpermute_b32 v35, v21, v25
	s_waitcnt lgkmcnt(0)
	v_add_f32_e32 v25, v25, v35
	ds_bpermute_b32 v35, v22, v25
	s_waitcnt lgkmcnt(0)
	v_add_f32_e32 v25, v25, v35
	ds_bpermute_b32 v35, v23, v25
	s_waitcnt lgkmcnt(0)
	v_add_f32_e32 v25, v25, v35
	ds_bpermute_b32 v35, v24, v25
	s_waitcnt lgkmcnt(0)
	v_add_f32_e32 v25, v25, v35
	v_fmamk_f32 v25, v25, 0x3a800000, v5
	v_rsq_f32_e32 v48, v25
	s_nop 0
	v_pk_mul_f32 v[26:27], v[26:27], v[48:49] op_sel_hi:[1,0]
	v_pk_mul_f32 v[28:29], v[28:29], v[48:49] op_sel_hi:[1,0]
	v_pk_mul_f32 v[30:31], v[30:31], v[48:49] op_sel_hi:[1,0]
	v_pk_mul_f32 v[32:33], v[32:33], v[48:49] op_sel_hi:[1,0]
	v_pk_mul_f32 v[26:27], v[44:45], v[26:27]
	v_pk_mul_f32 v[28:29], v[46:47], v[28:29]
	v_cvt_pk_bf16_f32 v26, v26, v27
	v_cvt_pk_bf16_f32 v27, v28, v29
	global_store_dwordx2 v[14:15], v[26:27], off offset:-1024
	v_mov_b64_e32 v[26:27], v[148:149]
	v_mov_b64_e32 v[28:29], v[150:151]
	v_pk_mul_f32 v[26:27], v[26:27], v[30:31]
	v_pk_mul_f32 v[28:29], v[28:29], v[32:33]
	v_cvt_pk_bf16_f32 v26, v26, v27
	v_cvt_pk_bf16_f32 v27, v28, v29
	global_store_dwordx2 v[14:15], v[26:27], off offset:-512
	v_mov_b64_e32 v[26:27], v[152:153]
	v_mov_b64_e32 v[28:29], v[154:155]
	v_pk_mul_f32 v[30:31], v[36:37], v[48:49] op_sel_hi:[1,0]
	v_pk_mul_f32 v[32:33], v[38:39], v[48:49] op_sel_hi:[1,0]
	v_pk_mul_f32 v[26:27], v[26:27], v[30:31]
	v_pk_mul_f32 v[28:29], v[28:29], v[32:33]
	v_cvt_pk_bf16_f32 v26, v26, v27
	v_cvt_pk_bf16_f32 v27, v28, v29
	global_store_dwordx2 v[14:15], v[26:27], off
	v_mov_b64_e32 v[26:27], v[156:157]
	v_mov_b64_e32 v[28:29], v[158:159]
	v_pk_mul_f32 v[30:31], v[40:41], v[48:49] op_sel_hi:[1,0]
	v_pk_mul_f32 v[32:33], v[42:43], v[48:49] op_sel_hi:[1,0]
	v_pk_mul_f32 v[26:27], v[26:27], v[30:31]
	v_pk_mul_f32 v[28:29], v[28:29], v[32:33]
	v_cvt_pk_bf16_f32 v26, v26, v27
	v_cvt_pk_bf16_f32 v27, v28, v29
	global_store_dwordx2 v[14:15], v[26:27], off offset:512
	v_lshl_add_u64 v[14:15], v[14:15], 0, s[8:9]
	s_cbranch_scc1 .LBB0_1441

; #define LAS __attribute__((address_space(3)))
; __device__ __forceinline__ unsigned cvtpk(float lo, float hi) { typedef __bf16 bf2 __attribute__((ext_vector_type(2))); f32x2 v = {lo, hi}; bf2 b = __builtin_convertvector(v, bf2); return __builtin_bit_cast(unsigned, b); }
; template <int DIR, bool PASS2>
; __device__ __forceinline__ void s5_sub(LAS unsigned char* ulds, const bf16x8 (&bb)[8], const bf16x8 (&bc)[4], float lbr, float lbi, float& sr, float& si, f32x4& yacc, int sub, int lane) {
;     ...
;     u32x4 uw = {0u, 0u, 0u, 0u};
;     if (kq < 2) uw = *(const LAS u32x4*)(ulds + (sub * 16 + hq) * 32 + kq * 16);
;     const bf16x8 ua = __builtin_bit_cast(bf16x8, uw);
;     LAS float* xp = xlds + (4 * kq) * S5_XP + hq;
;     f32x4 xs[8];
; #pragma unroll
;     for (int nt = 0; nt < 8; ++nt) xs[nt] = __builtin_amdgcn_mfma_f32_16x16x32_bf16(ua, bb[nt], (f32x4){0.f, 0.f, 0.f, 0.f}, 0, 0, 0);
;     asm volatile("s_nop 15\n\ts_nop 15" : "+v"(xs[0]), "+v"(xs[1]), "+v"(xs[2]), "+v"(xs[3]), "+v"(xs[4]), "+v"(xs[5]), "+v"(xs[6]), "+v"(xs[7]));
; #pragma unroll
;     for (int nt = 0; nt < 8; ++nt) { xp[16 * nt] = xs[nt][0]; xp[16 * nt + S5_XP] = xs[nt][1]; xp[16 * nt + 2 * S5_XP] = xs[nt][2]; xp[16 * nt + 3 * S5_XP] = xs[nt][3]; }
;     asm volatile("s_waitcnt lgkmcnt(0)" ::: "memory");
;     const LAS float* xr = xlds + 2 * lane; LAS unsigned char* sw = slds + lane * 4;
; #pragma unroll
;     for (int q = 0; q < 16; ++q) {
;         const int jj = DIR ? 15 - q : q;
;         const f32x2 x = *(const LAS f32x2*)(xr + jj * S5_XP);
;         const float nr = lbr * sr - lbi * si + x[0], ni = lbr * si + lbi * sr + x[1]; sr = nr; si = ni;
;         if (PASS2) *(LAS unsigned*)(sw + jj * 272) = cvtpk(sr, si);
;     }
; __device__ __forceinline__ void s5h_pass2(PPtr P, int li, LAS unsigned char* lds, int gw, int NGW, int wave, int lane) {
;     ...
;                 bf16_t* drow = dst + (size_t)(sub * 16 + 4 * kq) * LDP;
;                 float yf[4] = {0.f, 0.f, 0.f, 0.f};
;                 if (dir) {
; #pragma unroll
;                     for (int i = 0; i < 4; ++i) yf[i] = bf1(drow[(size_t)i * LDP]);
;                 }
;                 f32x4 acc = {0.f, 0.f, 0.f, 0.f};
;                 if (dir == 0) s5_sub<0, true>(ulds, bb, bc, lbr, lbi, sr, si, acc, sub, lane); else s5_sub<1, true>(ulds, bb, bc, lbr, lbi, sr, si, acc, sub, lane);
.LBB0_1921:
	s_and_b64 s[10:11], s[52:53], exec
	s_cselect_b32 s10, s38, s70
	v_lshl_or_b32 v64, s10, 4, v76
	v_mul_lo_u32 v68, v64, s74
	v_cndmask_b32_e64 v50, 0, 1, s[66:67]
	v_lshl_add_u64 v[56:57], v[68:69], 1, v[94:95]
	v_cmp_ne_u32_e64 s[10:11], 1, v50
	s_andn2_b64 vcc, exec, s[66:67]
	s_mov_b64 s[68:69], -1
	s_cbranch_vccnz .LBB0_1927
	v_add_co_u32_e32 v50, vcc, 0x1000, v56
	s_nop 1
	v_addc_co_u32_e32 v51, vcc, 0, v57, vcc
	v_add_co_u32_e32 v52, vcc, 0x3000, v56
	s_nop 1
	v_addc_co_u32_e32 v53, vcc, 0, v57, vcc
	v_add_co_u32_e32 v62, vcc, 0x4000, v56
	s_nop 1
	v_addc_co_u32_e32 v63, vcc, 0, v57, vcc
	global_load_ushort v60, v[56:57], off
	global_load_ushort v58, v[50:51], off offset:2368
	global_load_ushort v59, v[52:53], off offset:640
	global_load_ushort v65, v[62:63], off offset:3008
	v_mov_b32_e32 v50, 0
	v_mov_b32_e32 v51, 0
	v_mov_b32_e32 v52, 0
	v_mov_b32_e32 v53, 0
	s_and_saveexec_b64 s[68:69], s[8:9]
	ds_read_b128 v[50:53], v91
	s_or_b64 exec, exec, s[68:69]
	s_waitcnt lgkmcnt(0)
	v_mfma_f32_16x16x32_bf16 v[106:109], v[50:53], v[2:5], 0
	v_add_u32_e32 v61, v67, v75
	v_add_u32_e32 v62, 0x1000, v61
	v_add_u32_e32 v61, 0x1400, v61
	v_mfma_f32_16x16x32_bf16 v[126:129], v[50:53], v[6:9], 0
	v_mul_f32_e32 v68, v101, v102
	v_add_u32_e32 v110, s27, v77
	v_mfma_f32_16x16x32_bf16 v[130:133], v[50:53], v[10:13], 0
	v_mfma_f32_16x16x32_bf16 v[134:137], v[50:53], v[14:17], 0
	v_mfma_f32_16x16x32_bf16 v[138:141], v[50:53], v[18:21], 0
	v_mfma_f32_16x16x32_bf16 v[142:145], v[50:53], v[22:25], 0
	v_mfma_f32_16x16x32_bf16 v[146:149], v[50:53], v[26:29], 0
	v_mfma_f32_16x16x32_bf16 v[50:53], v[50:53], v[30:33], 0
	s_nop 15
	s_nop 15
	ds_write2_b32 v62, v106, v126 offset1:16
	ds_write2_b32 v62, v107, v127 offset0:132 offset1:148
	ds_write2_b32 v61, v108, v128 offset0:8 offset1:24
	ds_write2_b32 v61, v109, v129 offset0:140 offset1:156
	ds_write2_b32 v62, v130, v134 offset0:32 offset1:48
	ds_write2_b32 v62, v131, v135 offset0:164 offset1:180
	ds_write2_b32 v61, v132, v136 offset0:40 offset1:56
	ds_write2_b32 v61, v133, v137 offset0:172 offset1:188
	ds_write2_b32 v62, v138, v142 offset0:64 offset1:80
	ds_write2_b32 v62, v139, v143 offset0:196 offset1:212
	ds_write2_b32 v61, v140, v144 offset0:72 offset1:88
	ds_write2_b32 v61, v141, v145 offset0:204 offset1:220
	ds_write2_b32 v62, v146, v50 offset0:96 offset1:112
	ds_write2_b32 v62, v147, v51 offset0:228 offset1:244
	ds_write2_b32 v61, v148, v52 offset0:104 offset1:120
	ds_write2_b32 v61, v149, v53 offset0:236 offset1:252
	v_add_u32_e32 v61, s27, v70
	s_waitcnt lgkmcnt(0)
	v_add_u32_e32 v105, 0x2800, v61
	ds_read2_b64 v[50:53], v105 offset0:156 offset1:222
	v_mul_f32_e32 v62, v101, v103
	v_pk_fma_f32 v[62:63], v[100:101], v[102:103], v[62:63] op_sel_hi:[1,1,0] neg_lo:[0,0,1] neg_hi:[0,0,1]
	v_pk_fma_f32 v[106:107], v[100:101], v[102:103], v[68:69] op_sel:[0,1,0] op_sel_hi:[1,0,0]
	v_add_u32_e32 v111, 0x2000, v61
	s_waitcnt lgkmcnt(0)
	v_pk_add_f32 v[62:63], v[62:63], v[52:53]
	v_pk_add_f32 v[52:53], v[106:107], v[52:53] op_sel:[0,1] op_sel_hi:[1,0]
	s_nop 0
	v_mov_b32_e32 v63, v52
	v_mul_f32_e32 v68, v101, v52
	v_cvt_pk_bf16_f32 v108, v62, v52
	v_pk_fma_f32 v[106:107], v[100:101], v[62:63], v[68:69] op_sel_hi:[1,1,0] neg_lo:[0,0,1] neg_hi:[0,0,1]
	v_mov_b32_e32 v53, v62
	v_mul_f32_e32 v62, v101, v62
	v_pk_fma_f32 v[52:53], v[100:101], v[52:53], v[62:63] op_sel_hi:[1,1,0]
	v_pk_add_f32 v[106:107], v[50:51], v[106:107]
	v_pk_add_f32 v[62:63], v[50:51], v[52:53] op_sel:[1,0] op_sel_hi:[0,1]
	ds_read2_b64 v[50:53], v105 offset0:24 offset1:90
	v_cvt_pk_bf16_f32 v63, v106, v62
	v_add_u32_e32 v68, 0x3e00, v110
	v_mov_b32_e32 v107, v62
	ds_write2_b32 v68, v63, v108 offset0:120 offset1:188
	v_mul_f32_e32 v68, v101, v62
	v_pk_fma_f32 v[108:109], v[100:101], v[106:107], v[68:69] op_sel_hi:[1,1,0] neg_lo:[0,0,1] neg_hi:[0,0,1]
	v_mov_b32_e32 v63, v106
	v_mul_f32_e32 v68, v101, v106
	v_pk_fma_f32 v[62:63], v[100:101], v[62:63], v[68:69] op_sel_hi:[1,1,0]
	s_waitcnt lgkmcnt(1)
	v_pk_add_f32 v[108:109], v[52:53], v[108:109]
	v_pk_add_f32 v[52:53], v[52:53], v[62:63] op_sel:[1,0] op_sel_hi:[0,1]
	v_mov_b32_e32 v109, v52
	v_mul_f32_e32 v62, v101, v52
	v_mov_b32_e32 v53, v108
	v_mul_f32_e32 v68, v101, v108
	v_cvt_pk_bf16_f32 v105, v108, v52
	v_pk_fma_f32 v[62:63], v[100:101], v[108:109], v[62:63] op_sel_hi:[1,1,0] neg_lo:[0,0,1] neg_hi:[0,0,1]
	v_pk_fma_f32 v[52:53], v[100:101], v[52:53], v[68:69] op_sel_hi:[1,1,0]
	v_pk_add_f32 v[62:63], v[50:51], v[62:63]
	v_pk_add_f32 v[106:107], v[50:51], v[52:53] op_sel:[1,0] op_sel_hi:[0,1]
	ds_read2_b64 v[50:53], v111 offset0:148 offset1:214
	v_cvt_pk_bf16_f32 v68, v62, v106
	v_add_u32_e32 v107, 0x3c00, v110
	v_mov_b32_e32 v63, v106
	ds_write2_b32 v107, v68, v105 offset0:112 offset1:180
	v_mul_f32_e32 v68, v101, v106
	v_pk_fma_f32 v[108:109], v[100:101], v[62:63], v[68:69] op_sel_hi:[1,1,0] neg_lo:[0,0,1] neg_hi:[0,0,1]
	v_mov_b32_e32 v107, v62
	v_mul_f32_e32 v62, v101, v62
	v_pk_fma_f32 v[62:63], v[100:101], v[106:107], v[62:63] op_sel_hi:[1,1,0]
	s_waitcnt lgkmcnt(1)
	v_pk_add_f32 v[108:109], v[52:53], v[108:109]
	v_pk_add_f32 v[52:53], v[52:53], v[62:63] op_sel:[1,0] op_sel_hi:[0,1]
	v_mov_b32_e32 v109, v52
	v_mul_f32_e32 v62, v101, v52
	v_mov_b32_e32 v53, v108
	v_mul_f32_e32 v68, v101, v108
	v_cvt_pk_bf16_f32 v105, v108, v52
	v_pk_fma_f32 v[62:63], v[100:101], v[108:109], v[62:63] op_sel_hi:[1,1,0] neg_lo:[0,0,1] neg_hi:[0,0,1]
	v_pk_fma_f32 v[52:53], v[100:101], v[52:53], v[68:69] op_sel_hi:[1,1,0]
	v_pk_add_f32 v[62:63], v[50:51], v[62:63]
	v_pk_add_f32 v[106:107], v[50:51], v[52:53] op_sel:[1,0] op_sel_hi:[0,1]
	ds_read2_b64 v[50:53], v111 offset0:16 offset1:82
	v_cvt_pk_bf16_f32 v68, v62, v106
	v_add_u32_e32 v107, 0x3a00, v110
	v_mov_b32_e32 v63, v106
	ds_write2_b32 v107, v68, v105 offset0:104 offset1:172
	v_mul_f32_e32 v68, v101, v106
	v_pk_fma_f32 v[108:109], v[100:101], v[62:63], v[68:69] op_sel_hi:[1,1,0] neg_lo:[0,0,1] neg_hi:[0,0,1]
	v_mov_b32_e32 v107, v62
	v_mul_f32_e32 v62, v101, v62
	v_pk_fma_f32 v[62:63], v[100:101], v[106:107], v[62:63] op_sel_hi:[1,1,0]
	s_waitcnt lgkmcnt(1)
; #define LAS __attribute__((address_space(3)))
; __device__ __forceinline__ unsigned cvtpk(float lo, float hi) { typedef __bf16 bf2 __attribute__((ext_vector_type(2))); f32x2 v = {lo, hi}; bf2 b = __builtin_convertvector(v, bf2); return __builtin_bit_cast(unsigned, b); }
; template <int DIR, bool PASS2>
; __device__ __forceinline__ void s5_sub(LAS unsigned char* ulds, const bf16x8 (&bb)[8], const bf16x8 (&bc)[4], float lbr, float lbi, float& sr, float& si, f32x4& yacc, int sub, int lane) {
;     ...
;     const LAS float* xr = xlds + 2 * lane; LAS unsigned char* sw = slds + lane * 4;
; #pragma unroll
;     for (int q = 0; q < 16; ++q) {
;         const int jj = DIR ? 15 - q : q;
;         const f32x2 x = *(const LAS f32x2*)(xr + jj * S5_XP);
;         const float nr = lbr * sr - lbi * si + x[0], ni = lbr * si + lbi * sr + x[1]; sr = nr; si = ni;
;         if (PASS2) *(LAS unsigned*)(sw + jj * 272) = cvtpk(sr, si);
;     }
;     if (PASS2) {
;         asm volatile("s_waitcnt lgkmcnt(0)" ::: "memory");
;         f32x4 acc = DIR ? yacc : (f32x4){0.f, 0.f, 0.f, 0.f};
;         const LAS unsigned char* sa = slds + hq * 272 + kq * 16;
; #pragma unroll
;         for (int ks = 0; ks < 4; ++ks) { const bf16x8 a = *(const LAS bf16x8*)(sa + ks * 64); acc = __builtin_amdgcn_mfma_f32_16x16x32_bf16(a, bc[ks], acc, 0, 0, 0); }
;         yacc = acc;
; __device__ __forceinline__ void s5h_pass2(PPtr P, int li, LAS unsigned char* lds, int gw, int NGW, int wave, int lane) {
;     ...
;                 if (dir) {
; #pragma unroll
;                     for (int i = 0; i < 4; ++i) yf[i] = bf1(drow[(size_t)i * LDP]);
;                 }
	v_pk_add_f32 v[108:109], v[52:53], v[108:109]
	v_pk_add_f32 v[52:53], v[52:53], v[62:63] op_sel:[1,0] op_sel_hi:[0,1]
	v_mov_b32_e32 v109, v52
	v_mul_f32_e32 v62, v101, v52
	v_mov_b32_e32 v53, v108
	v_mul_f32_e32 v68, v101, v108
	v_cvt_pk_bf16_f32 v105, v108, v52
	v_pk_fma_f32 v[62:63], v[100:101], v[108:109], v[62:63] op_sel_hi:[1,1,0] neg_lo:[0,0,1] neg_hi:[0,0,1]
	v_pk_fma_f32 v[52:53], v[100:101], v[52:53], v[68:69] op_sel_hi:[1,1,0]
	v_add_u32_e32 v111, 0x1800, v61
	v_pk_add_f32 v[62:63], v[50:51], v[62:63]
	v_pk_add_f32 v[106:107], v[50:51], v[52:53] op_sel:[1,0] op_sel_hi:[0,1]
	ds_read2_b64 v[50:53], v111 offset0:140 offset1:206
	v_cvt_pk_bf16_f32 v68, v62, v106
	v_add_u32_e32 v107, 0x3800, v110
	v_mov_b32_e32 v63, v106
	ds_write2_b32 v107, v68, v105 offset0:96 offset1:164
	v_mul_f32_e32 v68, v101, v106
	v_pk_fma_f32 v[108:109], v[100:101], v[62:63], v[68:69] op_sel_hi:[1,1,0] neg_lo:[0,0,1] neg_hi:[0,0,1]
	v_mov_b32_e32 v107, v62
	v_mul_f32_e32 v62, v101, v62
	v_pk_fma_f32 v[62:63], v[100:101], v[106:107], v[62:63] op_sel_hi:[1,1,0]
	s_waitcnt lgkmcnt(1)
	v_pk_add_f32 v[108:109], v[52:53], v[108:109]
	v_pk_add_f32 v[52:53], v[52:53], v[62:63] op_sel:[1,0] op_sel_hi:[0,1]
	v_mov_b32_e32 v109, v52
	v_mul_f32_e32 v62, v101, v52
	v_mov_b32_e32 v53, v108
	v_mul_f32_e32 v68, v101, v108
	v_cvt_pk_bf16_f32 v105, v108, v52
	v_pk_fma_f32 v[62:63], v[100:101], v[108:109], v[62:63] op_sel_hi:[1,1,0] neg_lo:[0,0,1] neg_hi:[0,0,1]
	v_pk_fma_f32 v[52:53], v[100:101], v[52:53], v[68:69] op_sel_hi:[1,1,0]
	v_pk_add_f32 v[62:63], v[50:51], v[62:63]
	v_pk_add_f32 v[106:107], v[50:51], v[52:53] op_sel:[1,0] op_sel_hi:[0,1]
	ds_read2_b64 v[50:53], v111 offset0:8 offset1:74
	v_cvt_pk_bf16_f32 v68, v62, v106
	v_add_u32_e32 v107, 0x3600, v110
	v_mov_b32_e32 v63, v106
	ds_write2_b32 v107, v68, v105 offset0:88 offset1:156
	v_mul_f32_e32 v68, v101, v106
	v_pk_fma_f32 v[108:109], v[100:101], v[62:63], v[68:69] op_sel_hi:[1,1,0] neg_lo:[0,0,1] neg_hi:[0,0,1]
	v_mov_b32_e32 v107, v62
	v_mul_f32_e32 v62, v101, v62
	v_pk_fma_f32 v[62:63], v[100:101], v[106:107], v[62:63] op_sel_hi:[1,1,0]
	s_waitcnt lgkmcnt(1)
	v_pk_add_f32 v[108:109], v[52:53], v[108:109]
	v_pk_add_f32 v[52:53], v[52:53], v[62:63] op_sel:[1,0] op_sel_hi:[0,1]
	v_mov_b32_e32 v109, v52
	v_mul_f32_e32 v62, v101, v52
	v_mov_b32_e32 v53, v108
	v_mul_f32_e32 v68, v101, v108
	v_cvt_pk_bf16_f32 v105, v108, v52
	v_pk_fma_f32 v[62:63], v[100:101], v[108:109], v[62:63] op_sel_hi:[1,1,0] neg_lo:[0,0,1] neg_hi:[0,0,1]
	v_pk_fma_f32 v[52:53], v[100:101], v[52:53], v[68:69] op_sel_hi:[1,1,0]
	v_add_u32_e32 v61, 0x1000, v61
	v_pk_add_f32 v[62:63], v[50:51], v[62:63]
	v_pk_add_f32 v[106:107], v[50:51], v[52:53] op_sel:[1,0] op_sel_hi:[0,1]
	ds_read2_b64 v[50:53], v61 offset0:132 offset1:198
	v_cvt_pk_bf16_f32 v68, v62, v106
	v_add_u32_e32 v107, 0x3400, v110
	v_mov_b32_e32 v63, v106
	ds_write2_b32 v107, v68, v105 offset0:80 offset1:148
	v_mul_f32_e32 v68, v101, v106
	v_pk_fma_f32 v[108:109], v[100:101], v[62:63], v[68:69] op_sel_hi:[1,1,0] neg_lo:[0,0,1] neg_hi:[0,0,1]
	v_mov_b32_e32 v107, v62
	v_mul_f32_e32 v62, v101, v62
	v_pk_fma_f32 v[62:63], v[100:101], v[106:107], v[62:63] op_sel_hi:[1,1,0]
	s_waitcnt lgkmcnt(1)
	v_pk_add_f32 v[108:109], v[52:53], v[108:109]
	v_pk_add_f32 v[52:53], v[52:53], v[62:63] op_sel:[1,0] op_sel_hi:[0,1]
	v_mov_b32_e32 v109, v52
	v_mul_f32_e32 v62, v101, v52
	v_mov_b32_e32 v53, v108
	v_mul_f32_e32 v68, v101, v108
	v_cvt_pk_bf16_f32 v105, v108, v52
	v_pk_fma_f32 v[62:63], v[100:101], v[108:109], v[62:63] op_sel_hi:[1,1,0] neg_lo:[0,0,1] neg_hi:[0,0,1]
	v_pk_fma_f32 v[52:53], v[100:101], v[52:53], v[68:69] op_sel_hi:[1,1,0]
	v_pk_add_f32 v[62:63], v[50:51], v[62:63]
	v_pk_add_f32 v[106:107], v[50:51], v[52:53] op_sel:[1,0] op_sel_hi:[0,1]
	v_cvt_pk_bf16_f32 v50, v62, v106
	v_add_u32_e32 v51, 0x3200, v110
	ds_write2_b32 v51, v50, v105 offset0:72 offset1:140
	ds_read2_b64 v[50:53], v61 offset1:66
	v_mov_b32_e32 v63, v106
	v_pk_mul_f32 v[108:109], v[100:101], v[62:63]
	v_mov_b32_e32 v107, v62
	v_mul_f32_e32 v62, v101, v62
	v_pk_fma_f32 v[62:63], v[100:101], v[106:107], v[62:63] op_sel_hi:[1,1,0]
	s_waitcnt lgkmcnt(0)
	v_pk_add_f32 v[62:63], v[52:53], v[62:63] op_sel:[1,0] op_sel_hi:[0,1]
	v_sub_f32_e32 v53, v108, v109
	v_add_f32_e32 v52, v52, v53
	v_cvt_pk_bf16_f32 v61, v52, v62
	v_pk_mul_f32 v[62:63], v[54:55], v[62:63] op_sel_hi:[1,0]
	s_nop 0
	v_pk_fma_f32 v[106:107], v[100:101], v[52:53], v[62:63] op_sel_hi:[1,0,1] neg_lo:[0,0,1] neg_hi:[0,0,1]
	v_pk_fma_f32 v[52:53], v[100:101], v[52:53], v[62:63] op_sel_hi:[1,0,1]
	s_nop 0
	v_mov_b32_e32 v107, v53
	v_pk_add_f32 v[62:63], v[50:51], v[106:107]
	v_add_u32_e32 v51, 0x3000, v110
	v_cvt_pk_bf16_f32 v50, v62, v63
	ds_write2_b32 v51, v50, v61 offset0:64 offset1:132
	s_waitcnt lgkmcnt(0)
	v_add_u32_e32 v61, v112, v113
	ds_read_b128 v[50:53], v61 offset:12544
	ds_read_b128 v[106:109], v61 offset:12608
	s_waitcnt lgkmcnt(1)
	v_mfma_f32_16x16x32_bf16 v[50:53], v[50:53], v[34:37], 0
	ds_read_b128 v[126:129], v61 offset:12672
	s_waitcnt lgkmcnt(1)
	v_mfma_f32_16x16x32_bf16 v[50:53], v[106:109], v[38:41], v[50:53]
	ds_read_b128 v[106:109], v61 offset:12736
	s_waitcnt lgkmcnt(0)
	s_waitcnt vmcnt(3)
	v_lshlrev_b32_e32 v60, 16, v60
	s_waitcnt vmcnt(2)
	v_lshlrev_b32_e32 v61, 16, v58
	s_waitcnt lgkmcnt(1)
	v_mfma_f32_16x16x32_bf16 v[50:53], v[126:129], v[42:45], v[50:53]
	s_waitcnt vmcnt(1)
	v_lshlrev_b32_e32 v58, 16, v59
	s_waitcnt vmcnt(0)
	v_lshlrev_b32_e32 v59, 16, v65
	s_waitcnt lgkmcnt(0)
	v_mfma_f32_16x16x32_bf16 v[50:53], v[106:109], v[46:49], v[50:53]

; __device__ __forceinline__ void resnorm_rows(const float* hin, const bf16_t* tmp, const float* g1, float* hout, const float* g2, bf16_t* xn, int gw, int NGW, int lane) {
;     for (int row = gw; row < NTOK; row += NGW) {
;         const u32x2* tr = (const u32x2*)(tmp + (size_t)row * DMODEL) + lane; f32x4 t[4]; float ss = 0.f;
; #pragma unroll
;         for (int j = 0; j < 4; ++j) { const u32x2 w = __builtin_nontemporal_load(tr + 64 * j); t[j] = (f32x4){bflo(w.x), bfhi(w.x), bflo(w.y), bfhi(w.y)}; ss += (t[j][0] * t[j][0] + t[j][1] * t[j][1]) + (t[j][2] * t[j][2] + t[j][3] * t[j][3]); }
;         const float rs = __builtin_amdgcn_rsqf(wave_sum(ss) * (1.f / DMODEL) + EPSN);
;         const f32x4* hr = (const f32x4*)(hin + (size_t)row * DMODEL) + lane; f32x4* ho = (f32x4*)(hout + (size_t)row * DMODEL) + lane; float s2 = 0.f;
; #pragma unroll
;         for (int j = 0; j < 4; ++j) { const f32x4 gg = ((const f32x4*)g1)[lane + 64 * j]; f32x4 h = __builtin_nontemporal_load(hr + 64 * j);
; template <int ph> __device__ __forceinline__ void phase_body(LAS unsigned char* lds, int vcu, int NGW) {
;     ...
;                 resnorm_rows(li == 0 ? P->in[0] : P->out, tmp1, P->in[2] + li * 1024, P->out, P->in[3] + li * 1024, xn, gw, NGW, lane);
.LBB0_2544:
	s_cmp_lt_i32 s24, 18
	s_cselect_b64 s[4:5], -1, 0
	s_cmp_gt_i32 s25, 17
	s_cselect_b64 s[6:7], -1, 0
	s_and_b64 s[4:5], s[4:5], s[6:7]
	s_andn2_b64 vcc, exec, s[4:5]
	s_cbranch_vccnz .LBB0_2616
	s_mov_b64 s[8:9], s[0:1]
	v_mov_b32_e32 v2, v1
	s_lshl_b32 s11, s33, 3
	v_readfirstlane_b32 s3, v2
	s_ashr_i32 s10, s3, 6
	s_add_i32 s3, s10, s11
	s_cmpk_gt_i32 s3, 0x3fff
	s_cbranch_scc1 .LBB0_2548
	s_waitcnt lgkmcnt(0)
	v_and_b32_e32 v18, 63, v2
	v_mbcnt_lo_u32_b32 v2, -1, 0
	v_mbcnt_hi_u32_b32 v2, -1, v2
	v_and_b32_e32 v3, 64, v2
	v_add_u32_e32 v3, 64, v3
	v_xor_b32_e32 v4, 1, v2
	v_cmp_lt_i32_e32 vcc, v4, v3
	s_load_dwordx4 s[16:19], s[8:9], 0x10
	s_load_dwordx4 s[4:7], s[8:9], 0x110
	v_cndmask_b32_e32 v4, v2, v4, vcc
	v_lshlrev_b32_e32 v22, 2, v4
	v_xor_b32_e32 v4, 2, v2
	v_cmp_lt_i32_e32 vcc, v4, v3
	s_waitcnt lgkmcnt(0)
	s_add_u32 s8, s18, 0x1000
	s_addc_u32 s9, s19, 0
	v_cndmask_b32_e32 v4, v2, v4, vcc
	v_lshlrev_b32_e32 v23, 2, v4
	v_xor_b32_e32 v4, 4, v2
	v_cmp_lt_i32_e32 vcc, v4, v3
	s_add_u32 s16, s16, 0x1000
	v_lshlrev_b32_e32 v20, 4, v18
	v_cndmask_b32_e32 v4, v2, v4, vcc
	v_lshlrev_b32_e32 v24, 2, v4
	v_xor_b32_e32 v4, 8, v2
	v_cmp_lt_i32_e32 vcc, v4, v3
	v_mov_b32_e32 v21, 0
	s_addc_u32 s17, s17, 0
	v_cndmask_b32_e32 v4, v2, v4, vcc
	v_lshlrev_b32_e32 v25, 2, v4
	v_xor_b32_e32 v4, 16, v2
	v_cmp_lt_i32_e32 vcc, v4, v3
	v_or_b32_e32 v12, 0x400, v20
	v_mov_b32_e32 v13, v21
	v_cndmask_b32_e32 v4, v2, v4, vcc
	v_lshlrev_b32_e32 v26, 2, v4
	v_xor_b32_e32 v4, 32, v2
	v_cmp_lt_i32_e32 vcc, v4, v3
	v_or_b32_e32 v14, 0x800, v20
	v_mov_b32_e32 v15, v21
	v_cndmask_b32_e32 v2, v2, v4, vcc
	v_or_b32_e32 v16, 0xc00, v20
	v_mov_b32_e32 v17, v21
	v_lshlrev_b32_e32 v27, 2, v2
	v_lshl_add_u64 v[2:3], s[16:17], 0, v[20:21]
	v_lshl_add_u64 v[4:5], s[16:17], 0, v[12:13]
	v_lshl_add_u64 v[6:7], s[16:17], 0, v[14:15]
	v_lshl_add_u64 v[8:9], s[16:17], 0, v[16:17]
	v_lshl_add_u64 v[10:11], s[8:9], 0, v[20:21]
	v_lshl_add_u64 v[12:13], s[8:9], 0, v[12:13]
	v_lshl_add_u64 v[14:15], s[8:9], 0, v[14:15]
	v_lshl_add_u64 v[16:17], s[8:9], 0, v[16:17]
	s_ashr_i32 s9, s10, 31
	s_ashr_i32 s16, s11, 31
	s_add_u32 s8, s10, s11
	s_addc_u32 s9, s9, s16
	s_lshl_b64 s[10:11], s[8:9], 11
	s_add_u32 s6, s6, s10
	v_lshlrev_b32_e32 v18, 3, v18
	v_mov_b32_e32 v19, v21
	s_addc_u32 s7, s7, s11
	v_lshl_add_u64 v[18:19], s[6:7], 0, v[18:19]
	s_mov_b64 s[6:7], 0x9d00600
	s_ashr_i32 s27, s26, 31
	v_lshl_add_u64 v[18:19], v[18:19], 0, s[6:7]
	s_lshl_b64 s[6:7], s[26:27], 11
	s_lshl_b64 s[8:9], s[8:9], 12
	s_add_u32 s4, s4, s8
	s_addc_u32 s5, s5, s9
	v_lshl_add_u64 v[20:21], s[4:5], 0, v[20:21]
	s_lshl_b64 s[4:5], s[26:27], 12
	s_mov_b64 s[8:9], 0x400
	s_mov_b64 s[10:11], 0x800
	s_mov_b64 s[16:17], 0xc00
	v_mov_b32_e32 v28, 0x358637bd
	s_mov_b32 s97, 0
.LBB0_2547:
	v_add_co_u32_e32 v38, vcc, 0xf6300000, v18
	s_add_i32 s3, s3, s26
	s_nop 0
	v_addc_co_u32_e32 v39, vcc, -1, v19, vcc
	s_cmp_lg_u32 s97, 0
	s_cbranch_scc0 .Lrn_first_ph17
	s_waitcnt vmcnt(8)
	s_branch .Lrn_go_ph17
.Lrn_first_ph17:
	s_mov_b32 s97, 1
	global_load_dwordx2 v[160:161], v[38:39], off offset:-1024 nt
	global_load_dwordx2 v[162:163], v[38:39], off offset:-512 nt
	global_load_dwordx2 v[164:165], v[38:39], off offset:-1536 nt
	global_load_dwordx2 v[166:167], v[38:39], off nt
	global_load_dwordx4 v[168:171], v[20:21], off nt
	global_load_dwordx4 v[172:175], v[20:21], off offset:1024 nt
	global_load_dwordx4 v[176:179], v[20:21], off offset:2048 nt
	global_load_dwordx4 v[180:183], v[20:21], off offset:3072 nt
	global_load_dwordx4 v[200:203], v[2:3], off
	global_load_dwordx4 v[120:123], v[4:5], off
	global_load_dwordx4 v[128:131], v[6:7], off
	global_load_dwordx4 v[136:139], v[8:9], off
	global_load_dwordx4 v[144:147], v[10:11], off
	global_load_dwordx4 v[148:151], v[12:13], off
	global_load_dwordx4 v[152:155], v[14:15], off
	global_load_dwordx4 v[156:159], v[16:17], off
	s_waitcnt vmcnt(0)
.Lrn_go_ph17:
	v_lshl_add_u64 v[196:197], v[38:39], 0, s[6:7]
	v_lshl_add_u64 v[198:199], v[20:21], 0, s[4:5]
	v_mov_b64_e32 v[40:41], v[160:161]
	v_mov_b64_e32 v[42:43], v[162:163]
	v_mov_b64_e32 v[44:45], v[164:165]
	v_mov_b64_e32 v[46:47], v[166:167]
	v_mov_b64_e32 v[34:35], v[168:169]
	v_mov_b64_e32 v[36:37], v[170:171]
	v_mov_b64_e32 v[124:125], v[172:173]
	v_mov_b64_e32 v[126:127], v[174:175]
	v_mov_b64_e32 v[132:133], v[176:177]
	v_mov_b64_e32 v[134:135], v[178:179]
	v_mov_b64_e32 v[140:141], v[180:181]
	v_mov_b64_e32 v[142:143], v[182:183]
	v_mov_b64_e32 v[30:31], v[200:201]
	v_mov_b64_e32 v[32:33], v[202:203]
	s_cmpk_lt_i32 s3, 0x4000
	s_cbranch_scc0 .Lrn_nopf_ph17
	global_load_dwordx2 v[160:161], v[196:197], off offset:-1024 nt
	global_load_dwordx2 v[162:163], v[196:197], off offset:-512 nt
	global_load_dwordx2 v[164:165], v[196:197], off offset:-1536 nt
	global_load_dwordx2 v[166:167], v[196:197], off nt
	global_load_dwordx4 v[168:171], v[198:199], off nt
	global_load_dwordx4 v[172:175], v[198:199], off offset:1024 nt
	global_load_dwordx4 v[176:179], v[198:199], off offset:2048 nt
	global_load_dwordx4 v[180:183], v[198:199], off offset:3072 nt
; __device__ __forceinline__ void resnorm_rows(const float* hin, const bf16_t* tmp, const float* g1, float* hout, const float* g2, bf16_t* xn, int gw, int NGW, int lane) {
;     for (int row = gw; row < NTOK; row += NGW) {
;         const u32x2* tr = (const u32x2*)(tmp + (size_t)row * DMODEL) + lane; f32x4 t[4]; float ss = 0.f;
; #pragma unroll
;         for (int j = 0; j < 4; ++j) { const u32x2 w = __builtin_nontemporal_load(tr + 64 * j); t[j] = (f32x4){bflo(w.x), bfhi(w.x), bflo(w.y), bfhi(w.y)}; ss += (t[j][0] * t[j][0] + t[j][1] * t[j][1]) + (t[j][2] * t[j][2] + t[j][3] * t[j][3]); }
;         const float rs = __builtin_amdgcn_rsqf(wave_sum(ss) * (1.f / DMODEL) + EPSN);
.Lrn_nopf_ph17:
	v_lshlrev_b32_e32 v49, 16, v41
	v_and_b32_e32 v51, 0xffff0000, v41
	v_and_b32_e32 v50, 0xffff0000, v40
	v_and_b32_e32 v39, 0xffff0000, v44
	v_and_b32_e32 v41, 0xffff0000, v45
	v_lshlrev_b32_e32 v48, 16, v40
	v_lshlrev_b32_e32 v52, 16, v42
	v_and_b32_e32 v53, 0xffff0000, v42
	v_lshlrev_b32_e32 v54, 16, v43
	v_and_b32_e32 v55, 0xffff0000, v43
	v_lshlrev_b32_e32 v38, 16, v44
	v_lshlrev_b32_e32 v40, 16, v45
	v_pk_mul_f32 v[42:43], v[50:51], v[50:51]
	v_mul_f32_e32 v62, v39, v39
	v_mul_f32_e32 v64, v41, v41
	v_lshlrev_b32_e32 v56, 16, v46
	v_and_b32_e32 v59, 0xffff0000, v46
	v_and_b32_e32 v58, s0, v46
	v_lshlrev_b32_e32 v60, 16, v47
	v_and_b32_e32 v61, 0xffff0000, v47
	v_mul_f32_e32 v44, v53, v53
	v_mul_f32_e32 v46, v55, v55
	v_pk_fma_f32 v[42:43], v[48:49], v[48:49], v[42:43]
	v_pk_fma_f32 v[62:63], v[38:39], v[38:39], v[62:63] op_sel_hi:[1,1,0]
	v_pk_fma_f32 v[64:65], v[40:41], v[40:41], v[64:65] op_sel_hi:[1,1,0]
	v_pk_mul_f32 v[66:67], v[58:59], v[58:59]
	v_pk_mul_f32 v[68:69], v[60:61], v[60:61]
	v_pk_fma_f32 v[44:45], v[52:53], v[52:53], v[44:45] op_sel_hi:[1,1,0]
	v_pk_fma_f32 v[46:47], v[54:55], v[54:55], v[46:47] op_sel_hi:[1,1,0]
	v_pk_add_f32 v[42:43], v[42:43], v[42:43] op_sel:[0,1] op_sel_hi:[1,0]
	v_pk_add_f32 v[62:63], v[62:63], v[64:65]
	v_mov_b32_e32 v45, v68
	v_mov_b32_e32 v47, v69
	v_mul_f32_e32 v63, v56, v56
	v_mov_b32_e32 v43, v67
	v_pk_add_f32 v[44:45], v[44:45], v[46:47]
	v_pk_add_f32 v[42:43], v[62:63], v[42:43]
	v_mov_b32_e32 v57, v59
	v_pk_add_f32 v[42:43], v[42:43], v[44:45]
	v_mov_b32_e32 v44, v48
	v_add_f32_e32 v29, v42, v43
	ds_bpermute_b32 v42, v22, v29
	v_mov_b32_e32 v45, v50
	v_mov_b32_e32 v50, v49
	s_waitcnt lgkmcnt(0)
	v_add_f32_e32 v29, v29, v42
	ds_bpermute_b32 v42, v23, v29
	s_waitcnt lgkmcnt(0)
	v_add_f32_e32 v29, v29, v42
	ds_bpermute_b32 v42, v24, v29
	s_waitcnt lgkmcnt(0)
	v_add_f32_e32 v29, v29, v42
	ds_bpermute_b32 v42, v25, v29
	s_waitcnt lgkmcnt(0)
	v_add_f32_e32 v29, v29, v42
	ds_bpermute_b32 v42, v26, v29
	s_waitcnt lgkmcnt(0)
	v_add_f32_e32 v29, v29, v42
	ds_bpermute_b32 v42, v27, v29
	s_waitcnt lgkmcnt(0)
; __device__ __forceinline__ unsigned cvtpk(float lo, float hi) { typedef __bf16 bf2 __attribute__((ext_vector_type(2))); f32x2 v = {lo, hi}; bf2 b = __builtin_convertvector(v, bf2); return __builtin_bit_cast(unsigned, b); }
; __device__ __forceinline__ void st16_wt(void* p, u32x4 v) { asm volatile("global_store_dwordx4 %0, %1, off sc1\n\ts_nop 4" :: "v"(p), "v"(v) : "memory"); }
; __device__ __forceinline__ void resnorm_rows(const float* hin, const bf16_t* tmp, const float* g1, float* hout, const float* g2, bf16_t* xn, int gw, int NGW, int lane) {
;     ...
;         const f32x4* hr = (const f32x4*)(hin + (size_t)row * DMODEL) + lane; f32x4* ho = (f32x4*)(hout + (size_t)row * DMODEL) + lane; float s2 = 0.f;
; #pragma unroll
;         for (int j = 0; j < 4; ++j) { const f32x4 gg = ((const f32x4*)g1)[lane + 64 * j]; f32x4 h = __builtin_nontemporal_load(hr + 64 * j);
;             h[0] += t[j][0] * rs * gg[0]; h[1] += t[j][1] * rs * gg[1]; h[2] += t[j][2] * rs * gg[2]; h[3] += t[j][3] * rs * gg[3];
;             st16_wt(ho + 64 * j, __builtin_bit_cast(u32x4, h)); t[j] = h; s2 += (h[0] * h[0] + h[1] * h[1]) + (h[2] * h[2] + h[3] * h[3]); }
;         if (g2) {
;             const float r2 = __builtin_amdgcn_rsqf(wave_sum(s2) * (1.f / DMODEL) + EPSN);
;             u32x2* o = (u32x2*)(xn + (size_t)row * DMODEL) + lane;
; #pragma unroll
;             for (int j = 0; j < 4; ++j) { const f32x4 gg = ((const f32x4*)g2)[lane + 64 * j]; u32x2 w; w.x = cvtpk(t[j][0] * r2 * gg[0], t[j][1] * r2 * gg[1]); w.y = cvtpk(t[j][2] * r2 * gg[2], t[j][3] * r2 * gg[3]); o[64 * j] = w; }
;         }
	v_add_f32_e32 v29, v29, v42
	v_fmamk_f32 v29, v29, 0x3a800000, v28
	v_rsq_f32_e32 v58, v29
	v_lshl_add_u64 v[42:43], v[20:21], 0, s[8:9]
	v_pk_mul_f32 v[38:39], v[58:59], v[38:39] op_sel_hi:[0,1]
	v_pk_mul_f32 v[40:41], v[58:59], v[40:41] op_sel_hi:[0,1]
	v_pk_fma_f32 v[30:31], v[30:31], v[38:39], v[34:35]
	v_pk_fma_f32 v[32:33], v[32:33], v[40:41], v[36:37]
	v_pk_mul_f32 v[44:45], v[58:59], v[44:45] op_sel_hi:[0,1]
	global_store_dwordx4 v[20:21], v[30:33], off sc1
	s_nop 4
	v_mov_b64_e32 v[34:35], v[120:121]
	v_mov_b64_e32 v[36:37], v[122:123]
	v_mov_b64_e32 v[38:39], v[124:125]
	v_mov_b64_e32 v[40:41], v[126:127]
	v_pk_mul_f32 v[46:47], v[58:59], v[50:51] op_sel_hi:[0,1]
	v_pk_mul_f32 v[48:49], v[58:59], v[52:53] op_sel_hi:[0,1]
	v_pk_mul_f32 v[50:51], v[58:59], v[54:55] op_sel_hi:[0,1]
	v_pk_mul_f32 v[52:53], v[58:59], v[56:57] op_sel_hi:[0,1]
	v_pk_mul_f32 v[54:55], v[58:59], v[60:61] op_sel_hi:[0,1]
	v_pk_fma_f32 v[34:35], v[34:35], v[44:45], v[38:39]
	v_pk_fma_f32 v[36:37], v[36:37], v[46:47], v[40:41]
	v_lshl_add_u64 v[46:47], v[20:21], 0, s[10:11]
	global_store_dwordx4 v[42:43], v[34:37], off sc1
	s_nop 4
	v_mov_b64_e32 v[38:39], v[128:129]
	v_mov_b64_e32 v[40:41], v[130:131]
	v_mov_b64_e32 v[42:43], v[132:133]
	v_mov_b64_e32 v[44:45], v[134:135]
	v_pk_fma_f32 v[38:39], v[38:39], v[48:49], v[42:43]
	v_pk_fma_f32 v[40:41], v[40:41], v[50:51], v[44:45]
	v_lshl_add_u64 v[50:51], v[20:21], 0, s[16:17]
	global_store_dwordx4 v[46:47], v[38:41], off sc1
	s_nop 4
	v_mov_b64_e32 v[42:43], v[136:137]
	v_mov_b64_e32 v[44:45], v[138:139]
	v_mov_b64_e32 v[46:47], v[140:141]
	v_mov_b64_e32 v[48:49], v[142:143]
	v_lshl_add_u64 v[20:21], v[20:21], 0, s[4:5]
	v_pk_fma_f32 v[42:43], v[52:53], v[42:43], v[46:47]
	v_pk_fma_f32 v[44:45], v[54:55], v[44:45], v[48:49]
	v_mov_b32_e32 v52, v31
	global_store_dwordx4 v[50:51], v[42:45], off sc1
	s_nop 4
	v_mov_b64_e32 v[46:47], v[144:145]
	v_mov_b64_e32 v[48:49], v[146:147]
	v_mov_b32_e32 v53, v33
	v_mov_b32_e32 v50, v30
	v_mov_b32_e32 v51, v32
	v_pk_mul_f32 v[52:53], v[52:53], v[52:53]
	v_mov_b32_e32 v54, v35
	v_mov_b32_e32 v55, v37
	v_pk_fma_f32 v[50:51], v[50:51], v[50:51], v[52:53]
	v_mov_b32_e32 v52, v34
	v_mov_b32_e32 v53, v36
	v_pk_mul_f32 v[54:55], v[54:55], v[54:55]
	v_pk_add_f32 v[50:51], v[50:51], v[50:51] op_sel_hi:[0,1]
	v_pk_fma_f32 v[52:53], v[52:53], v[52:53], v[54:55]
	v_mul_f32_e32 v50, v38, v38
	v_pk_add_f32 v[52:53], v[52:53], v[52:53] op_sel_hi:[0,1]
	v_mul_f32_e32 v52, v40, v40
	v_pk_fma_f32 v[54:55], v[38:39], v[38:39], v[50:51] op_sel_hi:[1,1,0]
	v_pk_fma_f32 v[56:57], v[40:41], v[40:41], v[52:53] op_sel_hi:[1,1,0]
	v_pk_mul_f32 v[58:59], v[42:43], v[42:43]
	v_pk_mul_f32 v[60:61], v[44:45], v[44:45]
	v_mov_b32_e32 v54, v58
	v_mov_b32_e32 v56, v59
	v_mov_b32_e32 v50, v60
	v_mov_b32_e32 v52, v61
	v_pk_add_f32 v[54:55], v[54:55], v[56:57]
	v_pk_add_f32 v[50:51], v[50:51], v[52:53]
	s_nop 0
	v_pk_add_f32 v[50:51], v[54:55], v[50:51]
	s_nop 0
	v_add_f32_e32 v29, v50, v51
	ds_bpermute_b32 v50, v22, v29
	s_waitcnt lgkmcnt(0)
	v_add_f32_e32 v29, v29, v50
	ds_bpermute_b32 v50, v23, v29
	s_waitcnt lgkmcnt(0)
	v_add_f32_e32 v29, v29, v50
	ds_bpermute_b32 v50, v24, v29
	s_waitcnt lgkmcnt(0)
	v_add_f32_e32 v29, v29, v50
	ds_bpermute_b32 v50, v25, v29
	s_waitcnt lgkmcnt(0)
	v_add_f32_e32 v29, v29, v50
	ds_bpermute_b32 v50, v26, v29
	s_waitcnt lgkmcnt(0)
	v_add_f32_e32 v29, v29, v50
	ds_bpermute_b32 v50, v27, v29
	s_waitcnt lgkmcnt(0)
	v_add_f32_e32 v29, v29, v50
	v_fmamk_f32 v29, v29, 0x3a800000, v28
	v_rsq_f32_e32 v50, v29
	s_nop 0
	v_pk_mul_f32 v[30:31], v[30:31], v[50:51] op_sel_hi:[1,0]
	v_pk_mul_f32 v[32:33], v[32:33], v[50:51] op_sel_hi:[1,0]
	v_pk_mul_f32 v[34:35], v[34:35], v[50:51] op_sel_hi:[1,0]
	v_pk_mul_f32 v[36:37], v[36:37], v[50:51] op_sel_hi:[1,0]
	v_pk_mul_f32 v[30:31], v[46:47], v[30:31]
	v_pk_mul_f32 v[32:33], v[48:49], v[32:33]
	v_cvt_pk_bf16_f32 v30, v30, v31
	v_cvt_pk_bf16_f32 v31, v32, v33
	global_store_dwordx2 v[18:19], v[30:31], off offset:-1536
	v_mov_b64_e32 v[30:31], v[148:149]
	v_mov_b64_e32 v[32:33], v[150:151]
	v_pk_mul_f32 v[30:31], v[30:31], v[34:35]
	v_pk_mul_f32 v[32:33], v[32:33], v[36:37]
	v_cvt_pk_bf16_f32 v30, v30, v31
	v_cvt_pk_bf16_f32 v31, v32, v33
	global_store_dwordx2 v[18:19], v[30:31], off offset:-1024
	v_mov_b64_e32 v[30:31], v[152:153]
	v_mov_b64_e32 v[32:33], v[154:155]
	v_pk_mul_f32 v[34:35], v[38:39], v[50:51] op_sel_hi:[1,0]
	v_pk_mul_f32 v[36:37], v[40:41], v[50:51] op_sel_hi:[1,0]
	v_pk_mul_f32 v[30:31], v[30:31], v[34:35]
	v_pk_mul_f32 v[32:33], v[32:33], v[36:37]
	v_cvt_pk_bf16_f32 v30, v30, v31
	v_cvt_pk_bf16_f32 v31, v32, v33
	global_store_dwordx2 v[18:19], v[30:31], off offset:-512
	v_mov_b64_e32 v[30:31], v[156:157]
	v_mov_b64_e32 v[32:33], v[158:159]
	v_pk_mul_f32 v[34:35], v[42:43], v[50:51] op_sel_hi:[1,0]
	v_pk_mul_f32 v[36:37], v[44:45], v[50:51] op_sel_hi:[1,0]
	v_pk_mul_f32 v[30:31], v[30:31], v[34:35]
	v_pk_mul_f32 v[32:33], v[32:33], v[36:37]
	v_cvt_pk_bf16_f32 v30, v30, v31
	v_cvt_pk_bf16_f32 v31, v32, v33
	global_store_dwordx2 v[18:19], v[30:31], off
	v_lshl_add_u64 v[18:19], v[18:19], 0, s[6:7]
	s_cbranch_scc1 .LBB0_2547

; __device__ __forceinline__ void resnorm_rows(const float* hin, const bf16_t* tmp, const float* g1, float* hout, const float* g2, bf16_t* xn, int gw, int NGW, int lane) {
;     for (int row = gw; row < NTOK; row += NGW) {
;         const u32x2* tr = (const u32x2*)(tmp + (size_t)row * DMODEL) + lane; f32x4 t[4]; float ss = 0.f;
; #pragma unroll
;         for (int j = 0; j < 4; ++j) { const u32x2 w = __builtin_nontemporal_load(tr + 64 * j); t[j] = (f32x4){bflo(w.x), bfhi(w.x), bflo(w.y), bfhi(w.y)}; ss += (t[j][0] * t[j][0] + t[j][1] * t[j][1]) + (t[j][2] * t[j][2] + t[j][3] * t[j][3]); }
;         const float rs = __builtin_amdgcn_rsqf(wave_sum(ss) * (1.f / DMODEL) + EPSN);
;         const f32x4* hr = (const f32x4*)(hin + (size_t)row * DMODEL) + lane; f32x4* ho = (f32x4*)(hout + (size_t)row * DMODEL) + lane; float s2 = 0.f;
; #pragma unroll
;         for (int j = 0; j < 4; ++j) { const f32x4 gg = ((const f32x4*)g1)[lane + 64 * j]; f32x4 h = __builtin_nontemporal_load(hr + 64 * j);
; template <int ph> __device__ __forceinline__ void phase_body(LAS unsigned char* lds, int vcu, int NGW) {
;     ...
;                 resnorm_rows(P->out, tmp2, P->in[4] + li * 1024, P->out, last ? nullptr : P->in[1] + (li + 1) * 1024, xn, gw, NGW, lane);
.LBB0_2864:
	s_cmp_lt_i32 s24, 21
	s_cselect_b64 s[2:3], -1, 0
	s_cmp_gt_i32 s25, 20
	s_cselect_b64 s[4:5], -1, 0
	s_and_b64 s[2:3], s[2:3], s[4:5]
	s_andn2_b64 vcc, exec, s[2:3]
	s_cbranch_vccnz .LBB0_2880
	v_mov_b32_e32 v2, v1
	s_lshl_b32 s3, s33, 3
	v_readfirstlane_b32 s2, v2
	s_ashr_i32 s2, s2, 6
	s_add_i32 s10, s2, s3
	s_cmpk_gt_i32 s10, 0x3fff
	s_cbranch_scc1 .LBB0_2868
	v_and_b32_e32 v4, 63, v2
	v_mbcnt_lo_u32_b32 v2, -1, 0
	v_mbcnt_hi_u32_b32 v2, -1, v2
	v_and_b32_e32 v3, 64, v2
	v_add_u32_e32 v3, 64, v3
	v_xor_b32_e32 v5, 1, v2
	v_cmp_lt_i32_e32 vcc, v5, v3
	s_load_dwordx4 s[4:7], s[0:1], 0x110
	s_load_dwordx2 s[8:9], s[0:1], 0x20
	v_cndmask_b32_e32 v5, v2, v5, vcc
	s_waitcnt lgkmcnt(0)
	v_lshlrev_b32_e32 v8, 2, v5
	v_xor_b32_e32 v5, 2, v2
	v_cmp_lt_i32_e32 vcc, v5, v3
	v_lshlrev_b32_e32 v6, 4, v4
	v_mov_b32_e32 v7, 0
	v_cndmask_b32_e32 v5, v2, v5, vcc
	v_lshlrev_b32_e32 v9, 2, v5
	v_xor_b32_e32 v5, 4, v2
	v_cmp_lt_i32_e32 vcc, v5, v3
	s_mov_b64 s[0:1], 0x1000
	v_lshlrev_b32_e32 v4, 3, v4
	v_cndmask_b32_e32 v5, v2, v5, vcc
	v_lshlrev_b32_e32 v10, 2, v5
	v_xor_b32_e32 v5, 8, v2
	v_cmp_lt_i32_e32 vcc, v5, v3
	v_mov_b32_e32 v14, 0x358637bd
	s_nop 0
	v_cndmask_b32_e32 v5, v2, v5, vcc
	v_lshlrev_b32_e32 v11, 2, v5
	v_xor_b32_e32 v5, 16, v2
	v_cmp_lt_i32_e32 vcc, v5, v3
	s_nop 1
	v_cndmask_b32_e32 v5, v2, v5, vcc
	v_lshlrev_b32_e32 v12, 2, v5
	v_xor_b32_e32 v5, 32, v2
	v_cmp_lt_i32_e32 vcc, v5, v3
	s_nop 1
	v_cndmask_b32_e32 v2, v2, v5, vcc
	v_lshlrev_b32_e32 v13, 2, v2
	v_lshl_add_u64 v[2:3], s[8:9], 0, v[6:7]
	v_lshl_add_u64 v[2:3], v[2:3], 0, s[0:1]
	s_ashr_i32 s0, s2, 31
	s_ashr_i32 s1, s3, 31
	s_add_u32 s2, s2, s3
	s_addc_u32 s3, s0, s1
	s_lshl_b64 s[0:1], s[2:3], 11
	s_add_u32 s0, s6, s0
	v_mov_b32_e32 v5, v7
	s_addc_u32 s1, s7, s1
	v_lshl_add_u64 v[4:5], s[0:1], 0, v[4:5]
	s_mov_b64 s[0:1], 0x9d00400
	s_ashr_i32 s27, s26, 31
	v_lshl_add_u64 v[4:5], v[4:5], 0, s[0:1]
	s_lshl_b64 s[0:1], s[26:27], 11
	s_lshl_b64 s[2:3], s[2:3], 12
	s_add_u32 s2, s4, s2
	s_addc_u32 s3, s5, s3
	v_lshl_add_u64 v[6:7], s[2:3], 0, v[6:7]
	s_lshl_b64 s[2:3], s[26:27], 12
	s_mov_b64 s[4:5], 0x400
	s_mov_b64 s[6:7], 0x800
	s_mov_b64 s[8:9], 0xc00
	s_mov_b32 s97, 0
.LBB0_2867:
	s_cmp_lg_u32 s97, 0
	s_cbranch_scc0 .Lrn_first_ph20
	s_waitcnt vmcnt(4)
	s_branch .Lrn_go_ph20
.Lrn_first_ph20:
	s_mov_b32 s97, 1
	global_load_dwordx2 v[160:161], v[4:5], off offset:-512 nt
	global_load_dwordx2 v[162:163], v[4:5], off nt
	global_load_dwordx2 v[164:165], v[4:5], off offset:-1024 nt
	global_load_dwordx2 v[166:167], v[4:5], off offset:512 nt
	global_load_dwordx4 v[168:171], v[6:7], off nt
	global_load_dwordx4 v[172:175], v[6:7], off offset:1024 nt
	global_load_dwordx4 v[176:179], v[6:7], off offset:2048 nt
	global_load_dwordx4 v[180:183], v[6:7], off offset:3072 nt
	global_load_dwordx4 v[200:203], v[2:3], off
	global_load_dwordx4 v[120:123], v[2:3], off offset:1024
	global_load_dwordx4 v[128:131], v[2:3], off offset:2048
	global_load_dwordx4 v[136:139], v[2:3], off offset:3072
	s_waitcnt vmcnt(0)
.Lrn_go_ph20:
	v_lshl_add_u64 v[196:197], v[4:5], 0, s[0:1]
	v_lshl_add_u64 v[198:199], v[6:7], 0, s[2:3]
	v_mov_b64_e32 v[24:25], v[160:161]
	v_mov_b64_e32 v[26:27], v[162:163]
	v_mov_b64_e32 v[28:29], v[164:165]
	v_mov_b64_e32 v[30:31], v[166:167]
	v_mov_b64_e32 v[20:21], v[168:169]
	v_mov_b64_e32 v[22:23], v[170:171]
	v_mov_b64_e32 v[124:125], v[172:173]
	v_mov_b64_e32 v[126:127], v[174:175]
	v_mov_b64_e32 v[132:133], v[176:177]
	v_mov_b64_e32 v[134:135], v[178:179]
	v_mov_b64_e32 v[140:141], v[180:181]
	v_mov_b64_e32 v[142:143], v[182:183]
	v_mov_b64_e32 v[16:17], v[200:201]
	v_mov_b64_e32 v[18:19], v[202:203]
	s_add_i32 s10, s10, s26
	v_lshl_add_u64 v[4:5], v[4:5], 0, s[0:1]
	s_cmpk_lt_i32 s10, 0x4000
	s_cbranch_scc0 .Lrn_nopf_ph20
	global_load_dwordx2 v[160:161], v[196:197], off offset:-512 nt
	global_load_dwordx2 v[162:163], v[196:197], off nt
	global_load_dwordx2 v[164:165], v[196:197], off offset:-1024 nt
	global_load_dwordx2 v[166:167], v[196:197], off offset:512 nt
	global_load_dwordx4 v[168:171], v[198:199], off nt
	global_load_dwordx4 v[172:175], v[198:199], off offset:1024 nt
	global_load_dwordx4 v[176:179], v[198:199], off offset:2048 nt
	global_load_dwordx4 v[180:183], v[198:199], off offset:3072 nt
; __device__ __forceinline__ void st16_wt(void* p, u32x4 v) { asm volatile("global_store_dwordx4 %0, %1, off sc1\n\ts_nop 4" :: "v"(p), "v"(v) : "memory"); }
; __device__ __forceinline__ void resnorm_rows(const float* hin, const bf16_t* tmp, const float* g1, float* hout, const float* g2, bf16_t* xn, int gw, int NGW, int lane) {
;     ...
;         const u32x2* tr = (const u32x2*)(tmp + (size_t)row * DMODEL) + lane; f32x4 t[4]; float ss = 0.f;
; #pragma unroll
;         for (int j = 0; j < 4; ++j) { const u32x2 w = __builtin_nontemporal_load(tr + 64 * j); t[j] = (f32x4){bflo(w.x), bfhi(w.x), bflo(w.y), bfhi(w.y)}; ss += (t[j][0] * t[j][0] + t[j][1] * t[j][1]) + (t[j][2] * t[j][2] + t[j][3] * t[j][3]); }
;         const float rs = __builtin_amdgcn_rsqf(wave_sum(ss) * (1.f / DMODEL) + EPSN);
;         const f32x4* hr = (const f32x4*)(hin + (size_t)row * DMODEL) + lane; f32x4* ho = (f32x4*)(hout + (size_t)row * DMODEL) + lane; float s2 = 0.f;
; #pragma unroll
;         for (int j = 0; j < 4; ++j) { const f32x4 gg = ((const f32x4*)g1)[lane + 64 * j]; f32x4 h = __builtin_nontemporal_load(hr + 64 * j);
;             h[0] += t[j][0] * rs * gg[0]; h[1] += t[j][1] * rs * gg[1]; h[2] += t[j][2] * rs * gg[2]; h[3] += t[j][3] * rs * gg[3];
;             st16_wt(ho + 64 * j, __builtin_bit_cast(u32x4, h)); t[j] = h; s2 += (h[0] * h[0] + h[1] * h[1]) + (h[2] * h[2] + h[3] * h[3]); }
.Lrn_nopf_ph20:
	v_lshlrev_b32_e32 v33, 16, v25
	v_lshlrev_b32_e32 v32, 16, v24
	v_and_b32_e32 v25, 0xffff0000, v25
	v_and_b32_e32 v24, 0xffff0000, v24
	v_lshlrev_b32_e32 v36, 16, v28
	v_and_b32_e32 v37, 0xffff0000, v28
	v_lshlrev_b32_e32 v28, 16, v29
	v_and_b32_e32 v29, 0xffff0000, v29
	v_lshlrev_b32_e32 v34, 16, v26
	v_and_b32_e32 v35, 0xffff0000, v26
	v_lshlrev_b32_e32 v26, 16, v27
	v_and_b32_e32 v27, 0xffff0000, v27
	v_pk_mul_f32 v[42:43], v[24:25], v[24:25]
	v_mul_f32_e32 v48, v37, v37
	v_mul_f32_e32 v50, v29, v29
	v_lshlrev_b32_e32 v38, 16, v30
	v_and_b32_e32 v41, 0xffff0000, v30
	v_and_b32_e32 v40, s0, v30
	v_lshlrev_b32_e32 v30, 16, v31
	v_and_b32_e32 v31, 0xffff0000, v31
	v_mul_f32_e32 v44, v35, v35
	v_mul_f32_e32 v46, v27, v27
	v_pk_fma_f32 v[42:43], v[32:33], v[32:33], v[42:43]
	v_pk_fma_f32 v[48:49], v[36:37], v[36:37], v[48:49] op_sel_hi:[1,1,0]
	v_pk_fma_f32 v[50:51], v[28:29], v[28:29], v[50:51] op_sel_hi:[1,1,0]
	v_pk_mul_f32 v[52:53], v[40:41], v[40:41]
	v_pk_mul_f32 v[54:55], v[30:31], v[30:31]
	v_pk_fma_f32 v[44:45], v[34:35], v[34:35], v[44:45] op_sel_hi:[1,1,0]
	v_pk_fma_f32 v[46:47], v[26:27], v[26:27], v[46:47] op_sel_hi:[1,1,0]
	v_pk_add_f32 v[42:43], v[42:43], v[42:43] op_sel:[0,1] op_sel_hi:[1,0]
	v_pk_add_f32 v[48:49], v[48:49], v[50:51]
	v_mov_b32_e32 v45, v54
	v_mov_b32_e32 v47, v55
	v_mul_f32_e32 v49, v38, v38
	v_mov_b32_e32 v43, v53
	v_pk_add_f32 v[44:45], v[44:45], v[46:47]
	v_pk_add_f32 v[42:43], v[48:49], v[42:43]
	s_nop 0
	v_pk_add_f32 v[42:43], v[42:43], v[44:45]
	s_nop 0
	v_add_f32_e32 v15, v42, v43
	ds_bpermute_b32 v39, v8, v15
	s_waitcnt lgkmcnt(0)
	v_add_f32_e32 v15, v15, v39
	ds_bpermute_b32 v39, v9, v15
	s_waitcnt lgkmcnt(0)
	v_add_f32_e32 v15, v15, v39
	ds_bpermute_b32 v39, v10, v15
	s_waitcnt lgkmcnt(0)
	v_add_f32_e32 v15, v15, v39
	ds_bpermute_b32 v39, v11, v15
	s_waitcnt lgkmcnt(0)
	v_add_f32_e32 v15, v15, v39
	ds_bpermute_b32 v39, v12, v15
	s_waitcnt lgkmcnt(0)
	v_add_f32_e32 v15, v15, v39
	ds_bpermute_b32 v39, v13, v15
	s_waitcnt lgkmcnt(0)
	v_add_f32_e32 v15, v15, v39
	v_fmamk_f32 v15, v15, 0x3a800000, v14
	v_rsq_f32_e32 v40, v15
	v_mov_b32_e32 v39, v41
	v_pk_mul_f32 v[36:37], v[40:41], v[36:37] op_sel_hi:[0,1]
	v_pk_mul_f32 v[28:29], v[40:41], v[28:29] op_sel_hi:[0,1]
	v_pk_fma_f32 v[18:19], v[18:19], v[28:29], v[22:23]
	v_pk_fma_f32 v[16:17], v[16:17], v[36:37], v[20:21]
	v_mov_b32_e32 v36, v32
	global_store_dwordx4 v[6:7], v[16:19], off sc1
	s_nop 4
	v_mov_b64_e32 v[16:17], v[120:121]
	v_mov_b64_e32 v[18:19], v[122:123]
	v_mov_b64_e32 v[20:21], v[124:125]
	v_mov_b64_e32 v[22:23], v[126:127]
	v_mov_b32_e32 v37, v24
	v_mov_b32_e32 v24, v33
	v_pk_mul_f32 v[32:33], v[40:41], v[36:37] op_sel_hi:[0,1]
	v_pk_mul_f32 v[24:25], v[40:41], v[24:25] op_sel_hi:[0,1]
	v_lshl_add_u64 v[28:29], v[6:7], 0, s[4:5]
	v_pk_mul_f32 v[26:27], v[40:41], v[26:27] op_sel_hi:[0,1]
	v_pk_fma_f32 v[16:17], v[16:17], v[32:33], v[20:21]
	v_pk_fma_f32 v[18:19], v[18:19], v[24:25], v[22:23]
	v_lshl_add_u64 v[24:25], v[6:7], 0, s[6:7]
	global_store_dwordx4 v[28:29], v[16:19], off sc1
	s_nop 4
	v_mov_b64_e32 v[16:17], v[128:129]
	v_mov_b64_e32 v[18:19], v[130:131]
	v_mov_b64_e32 v[20:21], v[132:133]
	v_mov_b64_e32 v[22:23], v[134:135]
	v_pk_mul_f32 v[28:29], v[40:41], v[34:35] op_sel_hi:[0,1]
	v_pk_fma_f32 v[16:17], v[16:17], v[28:29], v[20:21]
	v_pk_fma_f32 v[18:19], v[18:19], v[26:27], v[22:23]
	v_pk_mul_f32 v[26:27], v[40:41], v[30:31] op_sel_hi:[0,1]
	global_store_dwordx4 v[24:25], v[16:19], off sc1
	s_nop 4
	v_mov_b64_e32 v[16:17], v[136:137]
	v_mov_b64_e32 v[18:19], v[138:139]
	v_mov_b64_e32 v[20:21], v[140:141]
	v_mov_b64_e32 v[22:23], v[142:143]
	v_pk_mul_f32 v[28:29], v[40:41], v[38:39] op_sel_hi:[0,1]
	v_lshl_add_u64 v[24:25], v[6:7], 0, s[8:9]
	v_lshl_add_u64 v[6:7], v[6:7], 0, s[2:3]
	v_pk_fma_f32 v[16:17], v[28:29], v[16:17], v[20:21]
	v_pk_fma_f32 v[18:19], v[26:27], v[18:19], v[22:23]
	s_nop 0
	global_store_dwordx4 v[24:25], v[16:19], off sc1
	s_nop 4
	s_cbranch_scc1 .LBB0_2867

; __global__ void __launch_bounds__(512, 2) fwd_mega(Params Pv) {
	.amdhsa_kernel _Z8fwd_mega6Params
		.amdhsa_group_segment_fixed_size 0
		.amdhsa_private_segment_fixed_size 0
		.amdhsa_kernarg_size 552
		.amdhsa_user_sgpr_count 2
		.amdhsa_user_sgpr_dispatch_ptr 0
		.amdhsa_user_sgpr_queue_ptr 0
		.amdhsa_user_sgpr_kernarg_segment_ptr 1
		.amdhsa_user_sgpr_dispatch_id 0
		.amdhsa_user_sgpr_kernarg_preload_length 0
		.amdhsa_user_sgpr_kernarg_preload_offset 0
		.amdhsa_user_sgpr_private_segment_size 0
		.amdhsa_uses_dynamic_stack 0
		.amdhsa_enable_private_segment 0
		.amdhsa_system_sgpr_workgroup_id_x 1
		.amdhsa_system_sgpr_workgroup_id_y 0
		.amdhsa_system_sgpr_workgroup_id_z 0
		.amdhsa_system_sgpr_workgroup_info 0
		.amdhsa_system_vgpr_workitem_id 2
		.amdhsa_next_free_vgpr 230
		.amdhsa_next_free_sgpr 99
		.amdhsa_accum_offset 232
		.amdhsa_reserve_vcc 1
		.amdhsa_float_round_mode_32 0
		.amdhsa_float_round_mode_16_64 0
		.amdhsa_float_denorm_mode_32 3
		.amdhsa_float_denorm_mode_16_64 3
		.amdhsa_dx10_clamp 1
		.amdhsa_ieee_mode 1
		.amdhsa_fp16_overflow 0
		.amdhsa_tg_split 0
		.amdhsa_exception_fp_ieee_invalid_op 0
		.amdhsa_exception_fp_denorm_src 0
		.amdhsa_exception_fp_ieee_div_zero 0
		.amdhsa_exception_fp_ieee_overflow 0
		.amdhsa_exception_fp_ieee_underflow 0
		.amdhsa_exception_fp_ieee_inexact 0
		.amdhsa_exception_int_div_zero 0
	.end_amdhsa_kernel

; __global__ void __launch_bounds__(512, 2) fwd_mega(Params Pv) {
amdhsa.kernels:
  - .agpr_count:     0
    .args:
      - .offset:         0
        .size:           296
        .value_kind:     by_value
      - .offset:         296
        .size:           4
        .value_kind:     hidden_block_count_x
      - .offset:         300
        .size:           4
        .value_kind:     hidden_block_count_y
      - .offset:         304
        .size:           4
        .value_kind:     hidden_block_count_z
      - .offset:         308
        .size:           2
        .value_kind:     hidden_group_size_x
      - .offset:         310
        .size:           2
        .value_kind:     hidden_group_size_y
      - .offset:         312
        .size:           2
        .value_kind:     hidden_group_size_z
      - .offset:         314
        .size:           2
        .value_kind:     hidden_remainder_x
      - .offset:         316
        .size:           2
        .value_kind:     hidden_remainder_y
      - .offset:         318
        .size:           2
        .value_kind:     hidden_remainder_z
      - .offset:         336
        .size:           8
        .value_kind:     hidden_global_offset_x
      - .offset:         344
        .size:           8
        .value_kind:     hidden_global_offset_y
      - .offset:         352
        .size:           8
        .value_kind:     hidden_global_offset_z
      - .offset:         360
        .size:           2
        .value_kind:     hidden_grid_dims
      - .offset:         384
        .size:           8
        .value_kind:     hidden_multigrid_sync_arg
      - .offset:         416
        .size:           4
        .value_kind:     hidden_dynamic_lds_size
    .group_segment_fixed_size: 0
    .kernarg_segment_align: 8
    .kernarg_segment_size: 552
    .language:       OpenCL C
    .language_version:
      - 2
      - 0
    .max_flat_workgroup_size: 512
    .name:           _Z8fwd_mega6Params
    .private_segment_fixed_size: 0
    .sgpr_count:     105
    .sgpr_spill_count: 0
    .symbol:         _Z8fwd_mega6Params.kd
    .uniform_work_group_size: 1
    .uses_dynamic_stack: false
    .vgpr_count:     230
    .vgpr_spill_count: 0
    .wavefront_size: 64
